# SwiGLU epilogue hazard-pad nops trimmed; EpiRes epilogues: x+0 identity adds removed
# speedup vs baseline: 1.0034x; 1.0001x over previous
.LBB0_414:
	v_lshl_add_u32 v166, s55, 8, v170
	v_lshl_or_b32 v158, s54, 8, v197
	v_ashrrev_i32_e32 v167, 31, v166
	v_lshlrev_b64 v[120:121], 11, v[166:167]
	v_ashrrev_i32_e32 v159, 31, v158
	v_lshl_add_u64 v[160:161], s[42:43], 0, v[120:121]
	v_lshlrev_b64 v[120:121], 1, v[158:159]
	v_lshl_add_u64 v[194:195], v[160:161], 0, v[120:121]
	global_load_dwordx4 v[200:203], v[194:195], off
	global_load_dwordx4 v[144:147], v[194:195], off offset:256
	v_or_b32_e32 v190, 16, v166
	v_ashrrev_i32_e32 v191, 31, v190
	v_lshlrev_b64 v[122:123], 11, v[190:191]
	v_or_b32_e32 v162, 32, v166
	v_lshl_add_u64 v[122:123], s[42:43], 0, v[122:123]
	v_ashrrev_i32_e32 v163, 31, v162
	v_lshl_add_u64 v[192:193], v[122:123], 0, v[120:121]
	v_lshlrev_b64 v[122:123], 11, v[162:163]
	v_lshl_add_u64 v[122:123], s[42:43], 0, v[122:123]
	v_lshl_add_u64 v[164:165], v[122:123], 0, v[120:121]
	global_load_dwordx4 v[136:139], v[192:193], off
	global_load_dwordx4 v[128:131], v[192:193], off offset:256
	global_load_dwordx4 v[124:127], v[164:165], off
	global_load_dwordx4 v[120:123], v[164:165], off offset:256
	s_lshl_b32 s16, s54, 2
	s_ashr_i32 s17, s16, 31
	s_waitcnt vmcnt(0)
	v_lshlrev_b32_e32 v178, 16, v200
	v_and_b32_e32 v179, 0xffff0000, v200
	v_add_f32_e32 v140, v140, v178
	v_add_f32_e32 v141, v141, v179
	v_lshlrev_b32_e32 v178, 16, v201
	v_and_b32_e32 v179, 0xffff0000, v201
	v_add_f32_e32 v142, v142, v178
	v_add_f32_e32 v143, v143, v179
	v_lshlrev_b32_e32 v178, 16, v202
	v_and_b32_e32 v179, 0xffff0000, v202
	v_add_f32_e32 v178, v132, v178
	v_add_f32_e32 v179, v133, v179
	v_lshlrev_b32_e32 v132, 16, v203
	v_and_b32_e32 v133, 0xffff0000, v203
	v_add_f32_e32 v180, v134, v132
	v_add_f32_e32 v181, v135, v133
	v_cvt_pk_bf16_f32 v132, v140, v141
	s_nop 0
	v_mul_f32_e32 v134, v141, v141
	v_cvt_pk_bf16_f32 v133, v142, v143
	v_fmac_f32_e32 v134, v140, v140
	s_nop 0
	v_mul_f32_e32 v135, v143, v143
	v_fmac_f32_e32 v135, v142, v142
	v_add_f32_e32 v135, v134, v135
	v_cvt_pk_bf16_f32 v134, v178, v179
	s_nop 0
	s_nop 0
	v_mul_f32_e32 v140, v179, v179
	v_fmac_f32_e32 v140, v178, v178
	v_add_f32_e32 v140, v140, v135
	v_cvt_pk_bf16_f32 v135, v180, v181
	s_nop 0
	global_store_dwordx4 v[194:195], v[132:135], off
	v_mul_f32_e32 v141, v181, v181
	v_fmac_f32_e32 v141, v180, v180
	v_lshlrev_b32_e32 v132, 16, v144
	v_and_b32_e32 v133, 0xffff0000, v144
	v_add_f32_e32 v116, v116, v132
	v_add_f32_e32 v117, v117, v133
	v_lshlrev_b32_e32 v132, 16, v145
	v_and_b32_e32 v133, 0xffff0000, v145
	v_add_f32_e32 v118, v118, v132
	v_add_f32_e32 v119, v119, v133
	v_lshlrev_b32_e32 v132, 16, v146
	v_and_b32_e32 v133, 0xffff0000, v146
	v_add_f32_e32 v132, v112, v132
	v_add_f32_e32 v133, v113, v133
	v_lshlrev_b32_e32 v112, 16, v147
	v_and_b32_e32 v113, 0xffff0000, v147
	v_add_f32_e32 v134, v114, v112
	v_add_f32_e32 v135, v115, v113
	v_cvt_pk_bf16_f32 v112, v116, v117
	v_add_f32_e32 v140, v141, v140
	s_nop 0
	v_mul_f32_e32 v113, v117, v117
	v_fmac_f32_e32 v113, v116, v116
	v_add_f32_e32 v114, v113, v140
	v_cvt_pk_bf16_f32 v113, v118, v119
	s_nop 0
	s_nop 0
	v_mul_f32_e32 v115, v119, v119
	v_fmac_f32_e32 v115, v118, v118
	v_add_f32_e32 v115, v115, v114
	v_cvt_pk_bf16_f32 v114, v132, v133
	s_nop 0
	s_nop 0
	v_mul_f32_e32 v116, v133, v133
	v_fmac_f32_e32 v116, v132, v132
	v_add_f32_e32 v116, v116, v115
	v_cvt_pk_bf16_f32 v115, v134, v135
	s_nop 0
	global_store_dwordx4 v[194:195], v[112:115], off offset:256
	v_mul_f32_e32 v117, v135, v135
	v_fmac_f32_e32 v117, v134, v134
	v_and_b32_e32 v113, 64, v213
	v_xor_b32_e32 v112, 16, v213
	v_add_u32_e32 v113, 64, v113
	v_cmp_lt_i32_e32 vcc, v112, v113
	v_add_f32_e32 v116, v117, v116
	v_xor_b32_e32 v114, 32, v213
	v_cndmask_b32_e32 v112, v213, v112, vcc
	v_lshlrev_b32_e32 v140, 2, v112
	ds_bpermute_b32 v112, v140, v116
	v_cmp_lt_i32_e32 vcc, v114, v113
	s_waitcnt lgkmcnt(0)
	v_add_f32_e32 v112, v116, v112
	v_cndmask_b32_e32 v113, v213, v114, vcc
	v_lshlrev_b32_e32 v141, 2, v113
	ds_bpermute_b32 v113, v141, v112
	s_and_saveexec_b64 s[18:19], s[2:3]
	s_mov_b64 s[56:57], s[44:45]
	s_cbranch_execz .LBB0_416
	s_waitcnt lgkmcnt(0)
	v_add_f32_e32 v114, v112, v113
	v_lshlrev_b64 v[112:113], 6, v[166:167]
	v_lshl_add_u64 v[112:113], s[40:41], 0, v[112:113]
	v_lshl_add_u64 v[112:113], s[16:17], 2, v[112:113]
	s_lshl_b32 s90, s35, 2
	v_lshl_add_u64 v[112:113], v[112:113], 0, s[90:91]
	global_store_dword v[112:113], v114, off
.LBB0_416:
	s_or_b64 exec, exec, s[18:19]
	v_or_b32_e32 v132, 48, v166
	v_ashrrev_i32_e32 v133, 31, v132
	s_waitcnt lgkmcnt(0)
	v_lshlrev_b64 v[112:113], 11, v[132:133]
	v_lshl_add_u64 v[112:113], s[42:43], 0, v[112:113]
	v_lshl_add_u64 v[134:135], v[158:159], 1, v[112:113]
	global_load_dwordx4 v[116:119], v[134:135], off
	global_load_dwordx4 v[112:115], v[134:135], off offset:256
	v_lshlrev_b32_e32 v142, 16, v136
	v_and_b32_e32 v136, 0xffff0000, v136
	v_add_f32_e32 v109, v109, v136
	v_lshlrev_b32_e32 v136, 16, v137
	v_and_b32_e32 v137, 0xffff0000, v137
	v_add_f32_e32 v110, v110, v136
	v_add_f32_e32 v111, v111, v137
	v_lshlrev_b32_e32 v136, 16, v138
	v_and_b32_e32 v137, 0xffff0000, v138
	v_add_f32_e32 v136, v104, v136
	v_add_f32_e32 v137, v105, v137
	v_lshlrev_b32_e32 v104, 16, v139
	v_and_b32_e32 v105, 0xffff0000, v139
	v_add_f32_e32 v108, v108, v142
	v_add_f32_e32 v138, v106, v104
	v_add_f32_e32 v139, v107, v105
	v_cvt_pk_bf16_f32 v104, v108, v109
	s_nop 0
	v_mul_f32_e32 v106, v109, v109
	v_cvt_pk_bf16_f32 v105, v110, v111
	v_fmac_f32_e32 v106, v108, v108
	s_nop 0
	v_mul_f32_e32 v107, v111, v111
	v_fmac_f32_e32 v107, v110, v110
	v_add_f32_e32 v107, v106, v107
	v_cvt_pk_bf16_f32 v106, v136, v137
	s_nop 0
	s_nop 0
	v_mul_f32_e32 v108, v137, v137
	v_fmac_f32_e32 v108, v136, v136
	v_add_f32_e32 v108, v108, v107
	v_cvt_pk_bf16_f32 v107, v138, v139
	s_nop 0
	global_store_dwordx4 v[192:193], v[104:107], off
	v_mul_f32_e32 v109, v139, v139
	v_fmac_f32_e32 v109, v138, v138
	v_lshlrev_b32_e32 v104, 16, v128
	v_and_b32_e32 v105, 0xffff0000, v128
	v_add_f32_e32 v100, v100, v104
	v_add_f32_e32 v101, v101, v105
	v_lshlrev_b32_e32 v104, 16, v129
	v_and_b32_e32 v105, 0xffff0000, v129
	v_add_f32_e32 v102, v102, v104
	v_add_f32_e32 v103, v103, v105
	v_lshlrev_b32_e32 v104, 16, v130
	v_and_b32_e32 v105, 0xffff0000, v130
	v_add_f32_e32 v96, v96, v104
	v_add_f32_e32 v97, v97, v105
	v_lshlrev_b32_e32 v104, 16, v131
	v_and_b32_e32 v105, 0xffff0000, v131
	v_add_f32_e32 v104, v98, v104
	v_add_f32_e32 v105, v99, v105
	v_cvt_pk_bf16_f32 v98, v100, v101
	v_add_f32_e32 v108, v109, v108
	s_nop 0
	v_mul_f32_e32 v99, v101, v101
	v_fmac_f32_e32 v99, v100, v100
	v_add_f32_e32 v100, v99, v108
	v_cvt_pk_bf16_f32 v99, v102, v103
	s_nop 0
	s_nop 0
	v_mul_f32_e32 v101, v103, v103
	v_fmac_f32_e32 v101, v102, v102
	v_add_f32_e32 v101, v101, v100
	v_cvt_pk_bf16_f32 v100, v96, v97
	s_nop 0
	v_mul_f32_e32 v97, v97, v97
	v_fmac_f32_e32 v97, v96, v96
	v_add_f32_e32 v96, v97, v101
	v_mul_f32_e32 v97, v105, v105
	v_fmac_f32_e32 v97, v104, v104
	v_add_f32_e32 v96, v97, v96
	ds_bpermute_b32 v97, v140, v96
	s_waitcnt lgkmcnt(0)
	v_add_f32_e32 v96, v96, v97
	ds_bpermute_b32 v97, v141, v96
	v_cvt_pk_bf16_f32 v101, v104, v105
	s_nop 0
	global_store_dwordx4 v[192:193], v[98:101], off offset:256
	s_and_saveexec_b64 s[18:19], s[2:3]
	s_cbranch_execz .LBB0_418
	s_waitcnt lgkmcnt(0)
	v_add_f32_e32 v98, v96, v97
	v_lshlrev_b64 v[96:97], 6, v[190:191]
	v_lshl_add_u64 v[96:97], s[40:41], 0, v[96:97]
	v_lshl_add_u64 v[96:97], s[16:17], 2, v[96:97]
	s_lshl_b32 s90, s35, 2
	v_lshl_add_u64 v[96:97], v[96:97], 0, s[90:91]
	global_store_dword v[96:97], v98, off
.LBB0_418:
	s_or_b64 exec, exec, s[18:19]
	v_add_u32_e32 v104, 0x80, v166
	v_ashrrev_i32_e32 v105, 31, v104
	s_waitcnt lgkmcnt(0)
	v_lshlrev_b64 v[96:97], 11, v[104:105]
	v_lshl_add_u64 v[96:97], s[42:43], 0, v[96:97]
	v_lshl_add_u64 v[106:107], v[158:159], 1, v[96:97]
	global_load_dwordx4 v[100:103], v[106:107], off
	global_load_dwordx4 v[96:99], v[106:107], off offset:256
	v_lshlrev_b32_e32 v108, 16, v124
	v_and_b32_e32 v109, 0xffff0000, v124
	v_add_f32_e32 v92, v92, v108
	v_add_f32_e32 v93, v93, v109
	v_lshlrev_b32_e32 v108, 16, v125
	v_and_b32_e32 v109, 0xffff0000, v125
	v_add_f32_e32 v94, v94, v108
	v_add_f32_e32 v95, v95, v109
	v_lshlrev_b32_e32 v108, 16, v126
	v_and_b32_e32 v109, 0xffff0000, v126
	v_add_f32_e32 v108, v88, v108
	v_add_f32_e32 v109, v89, v109
	v_lshlrev_b32_e32 v88, 16, v127
	v_and_b32_e32 v89, 0xffff0000, v127
	v_add_f32_e32 v110, v90, v88
	v_add_f32_e32 v111, v91, v89
	v_cvt_pk_bf16_f32 v88, v92, v93
	s_nop 0
	v_mul_f32_e32 v90, v93, v93
	v_cvt_pk_bf16_f32 v89, v94, v95
	v_fmac_f32_e32 v90, v92, v92
	s_nop 0
	v_mul_f32_e32 v91, v95, v95
	v_fmac_f32_e32 v91, v94, v94
	v_add_f32_e32 v91, v90, v91
	v_cvt_pk_bf16_f32 v90, v108, v109
	s_nop 0
	s_nop 0
	v_mul_f32_e32 v92, v109, v109
	v_fmac_f32_e32 v92, v108, v108
	v_add_f32_e32 v92, v92, v91
	v_cvt_pk_bf16_f32 v91, v110, v111
	s_nop 0
	v_and_b32_e32 v94, 0xffff0000, v91
	v_sub_f32_e32 v94, v111, v94
	global_store_dwordx4 v[164:165], v[88:91], off
	v_mul_f32_e32 v93, v111, v111
	v_fmac_f32_e32 v93, v110, v110
	v_lshlrev_b32_e32 v88, 16, v120
	v_and_b32_e32 v89, 0xffff0000, v120
	v_add_f32_e32 v84, v84, v88
	v_add_f32_e32 v85, v85, v89
	v_lshlrev_b32_e32 v88, 16, v121
	v_and_b32_e32 v89, 0xffff0000, v121
	v_add_f32_e32 v86, v86, v88
	v_add_f32_e32 v87, v87, v89
	v_lshlrev_b32_e32 v88, 16, v122
	v_and_b32_e32 v89, 0xffff0000, v122
	v_add_f32_e32 v80, v80, v88
	v_add_f32_e32 v81, v81, v89
	v_lshlrev_b32_e32 v88, 16, v123
	v_and_b32_e32 v89, 0xffff0000, v123
	v_add_f32_e32 v88, v82, v88
	v_add_f32_e32 v89, v83, v89
	v_cvt_pk_bf16_f32 v82, v84, v85
	v_add_f32_e32 v92, v93, v92
	s_nop 0
	v_mul_f32_e32 v83, v85, v85
	v_fmac_f32_e32 v83, v84, v84
	v_add_f32_e32 v84, v83, v92
	v_cvt_pk_bf16_f32 v83, v86, v87
	s_nop 0
	s_nop 0
	v_mul_f32_e32 v85, v87, v87
	v_fmac_f32_e32 v85, v86, v86
	v_add_f32_e32 v85, v85, v84
	v_cvt_pk_bf16_f32 v84, v80, v81
	s_nop 0
	v_mul_f32_e32 v81, v81, v81
	v_fmac_f32_e32 v81, v80, v80
	v_add_f32_e32 v80, v81, v85
	v_mul_f32_e32 v81, v89, v89
	v_fmac_f32_e32 v81, v88, v88
	v_add_f32_e32 v80, v81, v80
	ds_bpermute_b32 v81, v140, v80
	s_waitcnt lgkmcnt(0)
	v_add_f32_e32 v80, v80, v81
	ds_bpermute_b32 v81, v141, v80
	v_cvt_pk_bf16_f32 v85, v88, v89
	s_nop 0
	global_store_dwordx4 v[164:165], v[82:85], off offset:256
	s_and_saveexec_b64 s[18:19], s[2:3]
	s_cbranch_execz .LBB0_420
	s_waitcnt lgkmcnt(0)
	v_add_f32_e32 v82, v80, v81
	v_lshlrev_b64 v[80:81], 6, v[162:163]
	v_lshl_add_u64 v[80:81], s[40:41], 0, v[80:81]
	v_lshl_add_u64 v[80:81], s[16:17], 2, v[80:81]
	s_lshl_b32 s90, s35, 2
	v_lshl_add_u64 v[80:81], v[80:81], 0, s[90:91]
	global_store_dword v[80:81], v82, off
.LBB0_420:
	s_or_b64 exec, exec, s[18:19]
	s_waitcnt lgkmcnt(0)
	v_lshl_add_u64 v[80:81], v[158:159], 1, v[160:161]
	s_mov_b64 s[18:19], 0x48000
	v_lshl_add_u64 v[88:89], v[80:81], 0, s[18:19]
	v_add_co_u32_e32 v80, vcc, 0x48000, v80
	s_waitcnt vmcnt(7)
	v_lshlrev_b32_e32 v90, 16, v116
	v_addc_co_u32_e32 v81, vcc, 0, v81, vcc
	global_load_dwordx4 v[84:87], v[80:81], off
	s_nop 0
	global_load_dwordx4 v[80:83], v[88:89], off offset:256
	v_and_b32_e32 v91, 0xffff0000, v116
	v_add_f32_e32 v76, v76, v90
	v_add_f32_e32 v77, v77, v91
	v_lshlrev_b32_e32 v90, 16, v117
	v_and_b32_e32 v91, 0xffff0000, v117
	v_add_f32_e32 v78, v78, v90
	v_add_f32_e32 v79, v79, v91
	v_lshlrev_b32_e32 v90, 16, v118
	v_and_b32_e32 v91, 0xffff0000, v118
	v_add_f32_e32 v90, v72, v90
	v_add_f32_e32 v91, v73, v91
	v_lshlrev_b32_e32 v72, 16, v119
	v_and_b32_e32 v73, 0xffff0000, v119
	v_add_f32_e32 v92, v74, v72
	v_add_f32_e32 v93, v75, v73
	v_cvt_pk_bf16_f32 v72, v76, v77
	s_nop 0
	v_mul_f32_e32 v74, v77, v77
	v_cvt_pk_bf16_f32 v73, v78, v79
	v_fmac_f32_e32 v74, v76, v76
	s_nop 0
	v_mul_f32_e32 v75, v79, v79
	v_fmac_f32_e32 v75, v78, v78
	v_add_f32_e32 v75, v74, v75
	v_cvt_pk_bf16_f32 v74, v90, v91
	s_nop 0
	s_nop 0
	v_mul_f32_e32 v76, v91, v91
	v_fmac_f32_e32 v76, v90, v90
	v_add_f32_e32 v76, v76, v75
	v_cvt_pk_bf16_f32 v75, v92, v93
	s_nop 0
	global_store_dwordx4 v[134:135], v[72:75], off
	v_mul_f32_e32 v77, v93, v93
	v_fmac_f32_e32 v77, v92, v92
	s_waitcnt vmcnt(9)
	v_lshlrev_b32_e32 v72, 16, v112
	v_and_b32_e32 v73, 0xffff0000, v112
	v_add_f32_e32 v68, v68, v72
	v_add_f32_e32 v69, v69, v73
	v_lshlrev_b32_e32 v72, 16, v113
	v_and_b32_e32 v73, 0xffff0000, v113
	v_add_f32_e32 v70, v70, v72
	v_add_f32_e32 v71, v71, v73
	v_lshlrev_b32_e32 v72, 16, v114
	v_and_b32_e32 v73, 0xffff0000, v114
	v_add_f32_e32 v64, v64, v72
	v_add_f32_e32 v65, v65, v73
	v_lshlrev_b32_e32 v72, 16, v115
	v_and_b32_e32 v73, 0xffff0000, v115
	v_add_f32_e32 v72, v66, v72
	v_add_f32_e32 v73, v67, v73
	v_cvt_pk_bf16_f32 v66, v68, v69
	v_add_f32_e32 v76, v77, v76
	s_nop 0
	v_mul_f32_e32 v67, v69, v69
	v_fmac_f32_e32 v67, v68, v68
	v_add_f32_e32 v68, v67, v76
	v_cvt_pk_bf16_f32 v67, v70, v71
	s_nop 0
	s_nop 0
	v_mul_f32_e32 v69, v71, v71
	v_fmac_f32_e32 v69, v70, v70
	v_add_f32_e32 v69, v69, v68
	v_cvt_pk_bf16_f32 v68, v64, v65
	s_nop 0
	v_mul_f32_e32 v65, v65, v65
	v_fmac_f32_e32 v65, v64, v64
	v_add_f32_e32 v64, v65, v69
	v_mul_f32_e32 v65, v73, v73
	v_fmac_f32_e32 v65, v72, v72
	v_add_f32_e32 v64, v65, v64
	ds_bpermute_b32 v65, v140, v64
	s_waitcnt lgkmcnt(0)
	v_add_f32_e32 v64, v64, v65
	ds_bpermute_b32 v65, v141, v64
	v_cvt_pk_bf16_f32 v69, v72, v73
	s_nop 0
	global_store_dwordx4 v[134:135], v[66:69], off offset:256
	s_and_saveexec_b64 s[18:19], s[2:3]
	s_cbranch_execz .LBB0_422
	s_waitcnt lgkmcnt(0)
	v_add_f32_e32 v66, v64, v65
	v_lshlrev_b64 v[64:65], 6, v[132:133]
	v_lshl_add_u64 v[64:65], s[40:41], 0, v[64:65]
	v_lshl_add_u64 v[64:65], s[16:17], 2, v[64:65]
	s_lshl_b32 s90, s35, 2
	v_lshl_add_u64 v[64:65], v[64:65], 0, s[90:91]
	global_store_dword v[64:65], v66, off
.LBB0_422:
	s_or_b64 exec, exec, s[18:19]
	v_or_b32_e32 v72, 32, v104
	v_ashrrev_i32_e32 v73, 31, v72
	s_waitcnt lgkmcnt(0)
	v_lshlrev_b64 v[64:65], 11, v[72:73]
	v_lshl_add_u64 v[64:65], s[42:43], 0, v[64:65]
	v_lshl_add_u64 v[74:75], v[158:159], 1, v[64:65]
	global_load_dwordx4 v[68:71], v[74:75], off
	global_load_dwordx4 v[64:67], v[74:75], off offset:256
	s_waitcnt vmcnt(9)
	v_lshlrev_b32_e32 v76, 16, v100
	v_and_b32_e32 v77, 0xffff0000, v100
	v_add_f32_e32 v60, v60, v76
	v_add_f32_e32 v61, v61, v77
	v_lshlrev_b32_e32 v76, 16, v101
	v_and_b32_e32 v77, 0xffff0000, v101
	v_add_f32_e32 v62, v62, v76
	v_add_f32_e32 v63, v63, v77
	v_lshlrev_b32_e32 v76, 16, v102
	v_and_b32_e32 v77, 0xffff0000, v102
	v_add_f32_e32 v76, v56, v76
	v_add_f32_e32 v77, v57, v77
	v_lshlrev_b32_e32 v56, 16, v103
	v_and_b32_e32 v57, 0xffff0000, v103
	v_add_f32_e32 v78, v58, v56
	v_add_f32_e32 v79, v59, v57
	v_cvt_pk_bf16_f32 v56, v60, v61
	s_nop 0
	v_mul_f32_e32 v58, v61, v61
	v_cvt_pk_bf16_f32 v57, v62, v63
	v_fmac_f32_e32 v58, v60, v60
	s_nop 0
	v_mul_f32_e32 v59, v63, v63
	v_fmac_f32_e32 v59, v62, v62
	v_add_f32_e32 v59, v58, v59
	v_cvt_pk_bf16_f32 v58, v76, v77
	s_nop 0
	s_nop 0
	v_mul_f32_e32 v60, v77, v77
	v_fmac_f32_e32 v60, v76, v76
	v_add_f32_e32 v60, v60, v59
	v_cvt_pk_bf16_f32 v59, v78, v79
	s_nop 0
	global_store_dwordx4 v[106:107], v[56:59], off
	v_mul_f32_e32 v61, v79, v79
	v_fmac_f32_e32 v61, v78, v78
	s_waitcnt vmcnt(9)
	v_lshlrev_b32_e32 v56, 16, v96
	v_and_b32_e32 v57, 0xffff0000, v96
	v_add_f32_e32 v52, v52, v56
	v_add_f32_e32 v53, v53, v57
	v_lshlrev_b32_e32 v56, 16, v97
	v_and_b32_e32 v57, 0xffff0000, v97
	v_add_f32_e32 v54, v54, v56
	v_add_f32_e32 v55, v55, v57
	v_lshlrev_b32_e32 v56, 16, v98
	v_and_b32_e32 v57, 0xffff0000, v98
	v_add_f32_e32 v48, v48, v56
	v_add_f32_e32 v49, v49, v57
	v_lshlrev_b32_e32 v56, 16, v99
	v_and_b32_e32 v57, 0xffff0000, v99
	v_add_f32_e32 v56, v50, v56
	v_add_f32_e32 v57, v51, v57
	v_cvt_pk_bf16_f32 v50, v52, v53
	v_add_f32_e32 v60, v61, v60
	s_nop 0
	v_mul_f32_e32 v51, v53, v53
	v_fmac_f32_e32 v51, v52, v52
	v_add_f32_e32 v52, v51, v60
	v_cvt_pk_bf16_f32 v51, v54, v55
	s_nop 0
	s_nop 0
	v_mul_f32_e32 v53, v55, v55
	v_fmac_f32_e32 v53, v54, v54
	v_add_f32_e32 v53, v53, v52
	v_cvt_pk_bf16_f32 v52, v48, v49
	s_nop 0
	v_mul_f32_e32 v49, v49, v49
	v_fmac_f32_e32 v49, v48, v48
	v_add_f32_e32 v48, v49, v53
	v_mul_f32_e32 v49, v57, v57
	v_fmac_f32_e32 v49, v56, v56
	v_add_f32_e32 v48, v49, v48
	ds_bpermute_b32 v49, v140, v48
	s_waitcnt lgkmcnt(0)
	v_add_f32_e32 v48, v48, v49
	ds_bpermute_b32 v49, v141, v48
	v_cvt_pk_bf16_f32 v53, v56, v57
	s_nop 0
	global_store_dwordx4 v[106:107], v[50:53], off offset:256
	s_and_saveexec_b64 s[18:19], s[2:3]
	s_cbranch_execz .LBB0_424
	s_waitcnt lgkmcnt(0)
	v_add_f32_e32 v50, v48, v49
	v_lshlrev_b64 v[48:49], 6, v[104:105]
	v_lshl_add_u64 v[48:49], s[40:41], 0, v[48:49]
	v_lshl_add_u64 v[48:49], s[16:17], 2, v[48:49]
	s_lshl_b32 s90, s35, 2
	v_lshl_add_u64 v[48:49], v[48:49], 0, s[90:91]
	global_store_dword v[48:49], v50, off
.LBB0_424:
	s_or_b64 exec, exec, s[18:19]
	v_or_b32_e32 v56, 48, v104
	v_ashrrev_i32_e32 v57, 31, v56
	s_waitcnt lgkmcnt(0)
	v_lshlrev_b64 v[48:49], 11, v[56:57]
	v_lshl_add_u64 v[48:49], s[42:43], 0, v[48:49]
	v_lshl_add_u64 v[58:59], v[158:159], 1, v[48:49]
	global_load_dwordx4 v[52:55], v[58:59], off
	global_load_dwordx4 v[48:51], v[58:59], off offset:256
	s_waitcnt vmcnt(9)
	v_lshlrev_b32_e32 v60, 16, v84
	v_and_b32_e32 v61, 0xffff0000, v84
	v_add_f32_e32 v44, v44, v60
	v_add_f32_e32 v45, v45, v61
	v_lshlrev_b32_e32 v60, 16, v85
	v_and_b32_e32 v61, 0xffff0000, v85
	v_add_f32_e32 v46, v46, v60
	v_add_f32_e32 v47, v47, v61
	v_lshlrev_b32_e32 v60, 16, v86
	v_and_b32_e32 v61, 0xffff0000, v86
	v_add_f32_e32 v60, v40, v60
	v_add_f32_e32 v61, v41, v61
	v_lshlrev_b32_e32 v40, 16, v87
	v_and_b32_e32 v41, 0xffff0000, v87
	v_add_f32_e32 v62, v42, v40
	v_add_f32_e32 v63, v43, v41
	v_cvt_pk_bf16_f32 v40, v44, v45
	s_nop 0
	v_mul_f32_e32 v42, v45, v45
	v_cvt_pk_bf16_f32 v41, v46, v47
	v_fmac_f32_e32 v42, v44, v44
	s_nop 0
	v_mul_f32_e32 v43, v47, v47
	v_fmac_f32_e32 v43, v46, v46
	v_add_f32_e32 v43, v42, v43
	v_cvt_pk_bf16_f32 v42, v60, v61
	s_nop 0
	s_nop 0
	v_mul_f32_e32 v44, v61, v61
	v_fmac_f32_e32 v44, v60, v60
	v_add_f32_e32 v44, v44, v43
	v_cvt_pk_bf16_f32 v43, v62, v63
	s_nop 0
	v_and_b32_e32 v46, 0xffff0000, v43
	v_sub_f32_e32 v46, v63, v46
	global_store_dwordx4 v[88:89], v[40:43], off
	v_mul_f32_e32 v45, v63, v63
	v_fmac_f32_e32 v45, v62, v62
	s_waitcnt vmcnt(9)
	v_lshlrev_b32_e32 v40, 16, v80
	v_and_b32_e32 v41, 0xffff0000, v80
	v_add_f32_e32 v36, v36, v40
	v_add_f32_e32 v37, v37, v41
	v_lshlrev_b32_e32 v40, 16, v81
	v_and_b32_e32 v41, 0xffff0000, v81
	v_add_f32_e32 v38, v38, v40
	v_add_f32_e32 v39, v39, v41
	v_lshlrev_b32_e32 v40, 16, v82
	v_and_b32_e32 v41, 0xffff0000, v82
	v_add_f32_e32 v32, v32, v40
	v_add_f32_e32 v33, v33, v41
	v_lshlrev_b32_e32 v40, 16, v83
	v_and_b32_e32 v41, 0xffff0000, v83
	v_add_f32_e32 v40, v34, v40
	v_add_f32_e32 v41, v35, v41
	v_cvt_pk_bf16_f32 v34, v36, v37
	v_add_f32_e32 v44, v45, v44
	s_nop 0
	v_mul_f32_e32 v35, v37, v37
	v_fmac_f32_e32 v35, v36, v36
	v_add_f32_e32 v36, v35, v44
	v_cvt_pk_bf16_f32 v35, v38, v39
	s_nop 0
	v_and_b32_e32 v42, 0xffff0000, v35
	v_sub_f32_e32 v42, v39, v42
	s_nop 0
	v_mul_f32_e32 v37, v39, v39
	v_fmac_f32_e32 v37, v38, v38
	v_add_f32_e32 v37, v37, v36
	v_cvt_pk_bf16_f32 v36, v32, v33
	s_nop 0
	v_mul_f32_e32 v33, v33, v33
	v_fmac_f32_e32 v33, v32, v32
	v_add_f32_e32 v32, v33, v37
	v_mul_f32_e32 v33, v41, v41
	v_fmac_f32_e32 v33, v40, v40
	v_add_f32_e32 v32, v33, v32
	ds_bpermute_b32 v33, v140, v32
	s_waitcnt lgkmcnt(0)
	v_add_f32_e32 v32, v32, v33
	ds_bpermute_b32 v33, v141, v32
	v_cvt_pk_bf16_f32 v37, v40, v41
	s_nop 0
	v_lshlrev_b32_e32 v38, 16, v37
	v_sub_f32_e32 v38, v40, v38
	v_and_b32_e32 v39, 0xffff0000, v37
	v_sub_f32_e32 v39, v41, v39
	v_cvt_pk_bf16_f32 v38, v38, v39
	global_store_dwordx4 v[88:89], v[34:37], off offset:256
	s_and_saveexec_b64 s[18:19], s[2:3]
	s_cbranch_execz .LBB0_426
	v_or_b32_e32 v34, 16, v104
	v_ashrrev_i32_e32 v35, 31, v34
	s_waitcnt lgkmcnt(0)
	v_add_f32_e32 v36, v32, v33
	v_lshlrev_b64 v[32:33], 6, v[34:35]
	v_lshl_add_u64 v[32:33], s[40:41], 0, v[32:33]
	v_lshl_add_u64 v[32:33], s[16:17], 2, v[32:33]
	s_lshl_b32 s90, s35, 2
	v_lshl_add_u64 v[32:33], v[32:33], 0, s[90:91]
	global_store_dword v[32:33], v36, off
.LBB0_426:
	s_or_b64 exec, exec, s[18:19]
	s_waitcnt vmcnt(7)
	v_lshlrev_b32_e32 v32, 16, v68
	s_waitcnt lgkmcnt(0)
	v_and_b32_e32 v33, 0xffff0000, v68
	v_add_f32_e32 v28, v28, v32
	v_add_f32_e32 v29, v29, v33
	v_lshlrev_b32_e32 v32, 16, v69
	v_and_b32_e32 v33, 0xffff0000, v69
	v_add_f32_e32 v30, v30, v32
	v_add_f32_e32 v31, v31, v33
	v_lshlrev_b32_e32 v32, 16, v70
	v_and_b32_e32 v33, 0xffff0000, v70
	v_add_f32_e32 v32, v24, v32
	v_add_f32_e32 v33, v25, v33
	v_lshlrev_b32_e32 v24, 16, v71
	v_and_b32_e32 v25, 0xffff0000, v71
	v_add_f32_e32 v34, v26, v24
	v_add_f32_e32 v35, v27, v25
	v_cvt_pk_bf16_f32 v24, v28, v29
	s_nop 0
	v_mul_f32_e32 v26, v29, v29
	v_cvt_pk_bf16_f32 v25, v30, v31
	v_fmac_f32_e32 v26, v28, v28
	s_nop 0
	v_mul_f32_e32 v27, v31, v31
	v_fmac_f32_e32 v27, v30, v30
	v_add_f32_e32 v27, v26, v27
	v_cvt_pk_bf16_f32 v26, v32, v33
	s_nop 0
	s_nop 0
	v_mul_f32_e32 v28, v33, v33
	v_fmac_f32_e32 v28, v32, v32
	v_add_f32_e32 v28, v28, v27
	v_cvt_pk_bf16_f32 v27, v34, v35
	s_nop 0
	v_and_b32_e32 v30, 0xffff0000, v27
	v_sub_f32_e32 v30, v35, v30
	global_store_dwordx4 v[74:75], v[24:27], off
	v_mul_f32_e32 v29, v35, v35
	v_fmac_f32_e32 v29, v34, v34
	s_waitcnt vmcnt(7)
	v_lshlrev_b32_e32 v24, 16, v64
	v_and_b32_e32 v25, 0xffff0000, v64
	v_add_f32_e32 v20, v20, v24
	v_add_f32_e32 v21, v21, v25
	v_lshlrev_b32_e32 v24, 16, v65
	v_and_b32_e32 v25, 0xffff0000, v65
	v_add_f32_e32 v22, v22, v24
	v_add_f32_e32 v23, v23, v25
	v_lshlrev_b32_e32 v24, 16, v66
	v_and_b32_e32 v25, 0xffff0000, v66
	v_add_f32_e32 v16, v16, v24
	v_add_f32_e32 v17, v17, v25
	v_lshlrev_b32_e32 v24, 16, v67
	v_and_b32_e32 v25, 0xffff0000, v67
	v_add_f32_e32 v24, v18, v24
	v_add_f32_e32 v25, v19, v25
	v_cvt_pk_bf16_f32 v18, v20, v21
	v_add_f32_e32 v28, v29, v28
	s_nop 0
	v_mul_f32_e32 v19, v21, v21
	v_fmac_f32_e32 v19, v20, v20
	v_add_f32_e32 v20, v19, v28
	v_cvt_pk_bf16_f32 v19, v22, v23
	s_nop 0
	v_and_b32_e32 v26, 0xffff0000, v19
	v_sub_f32_e32 v26, v23, v26
	s_nop 0
	v_mul_f32_e32 v21, v23, v23
	v_fmac_f32_e32 v21, v22, v22
	v_add_f32_e32 v21, v21, v20
	v_cvt_pk_bf16_f32 v20, v16, v17
	s_nop 0
	v_mul_f32_e32 v17, v17, v17
	v_fmac_f32_e32 v17, v16, v16
	v_add_f32_e32 v16, v17, v21
	v_mul_f32_e32 v17, v25, v25
	v_fmac_f32_e32 v17, v24, v24
	v_add_f32_e32 v16, v17, v16
	ds_bpermute_b32 v17, v140, v16
	s_waitcnt lgkmcnt(0)
	v_add_f32_e32 v16, v16, v17
	ds_bpermute_b32 v17, v141, v16
	v_cvt_pk_bf16_f32 v21, v24, v25
	s_nop 0
	v_lshlrev_b32_e32 v22, 16, v21
	v_sub_f32_e32 v22, v24, v22
	v_and_b32_e32 v23, 0xffff0000, v21
	v_sub_f32_e32 v23, v25, v23
	v_cvt_pk_bf16_f32 v22, v22, v23
	global_store_dwordx4 v[74:75], v[18:21], off offset:256
	s_and_saveexec_b64 s[18:19], s[2:3]
	s_cbranch_execz .LBB0_428
	s_waitcnt lgkmcnt(0)
	v_add_f32_e32 v18, v16, v17
	v_lshlrev_b64 v[16:17], 6, v[72:73]
	v_lshl_add_u64 v[16:17], s[40:41], 0, v[16:17]
	v_lshl_add_u64 v[16:17], s[16:17], 2, v[16:17]
	s_lshl_b32 s90, s35, 2
	v_lshl_add_u64 v[16:17], v[16:17], 0, s[90:91]
	global_store_dword v[16:17], v18, off
.LBB0_428:
	s_or_b64 exec, exec, s[18:19]
	s_waitcnt vmcnt(5)
	v_lshlrev_b32_e32 v16, 16, v52
	s_waitcnt lgkmcnt(0)
	v_and_b32_e32 v17, 0xffff0000, v52
	v_add_f32_e32 v12, v12, v16
	v_add_f32_e32 v13, v13, v17
	v_lshlrev_b32_e32 v16, 16, v53
	v_and_b32_e32 v17, 0xffff0000, v53
	v_add_f32_e32 v14, v14, v16
	v_add_f32_e32 v15, v15, v17
	v_lshlrev_b32_e32 v16, 16, v54
	v_and_b32_e32 v17, 0xffff0000, v54
	v_add_f32_e32 v16, v8, v16
	v_add_f32_e32 v17, v9, v17
	v_lshlrev_b32_e32 v8, 16, v55
	v_and_b32_e32 v9, 0xffff0000, v55
	v_add_f32_e32 v18, v10, v8
	v_add_f32_e32 v19, v11, v9
	v_cvt_pk_bf16_f32 v8, v12, v13
	s_nop 0
	v_mul_f32_e32 v10, v13, v13
	v_cvt_pk_bf16_f32 v9, v14, v15
	v_fmac_f32_e32 v10, v12, v12
	s_nop 0
	v_mul_f32_e32 v11, v15, v15
	v_fmac_f32_e32 v11, v14, v14
	v_add_f32_e32 v11, v10, v11
	v_cvt_pk_bf16_f32 v10, v16, v17
	s_nop 0
	s_nop 0
	v_mul_f32_e32 v12, v17, v17
	v_fmac_f32_e32 v12, v16, v16
	v_add_f32_e32 v12, v12, v11
	v_cvt_pk_bf16_f32 v11, v18, v19
	s_nop 0
	v_and_b32_e32 v14, 0xffff0000, v11
	v_sub_f32_e32 v14, v19, v14
	global_store_dwordx4 v[58:59], v[8:11], off
	v_mul_f32_e32 v13, v19, v19
	v_fmac_f32_e32 v13, v18, v18
	s_waitcnt vmcnt(5)
	v_lshlrev_b32_e32 v8, 16, v48
	v_and_b32_e32 v9, 0xffff0000, v48
	v_add_f32_e32 v4, v4, v8
	v_add_f32_e32 v5, v5, v9
	v_lshlrev_b32_e32 v8, 16, v49
	v_and_b32_e32 v9, 0xffff0000, v49
	v_add_f32_e32 v6, v6, v8
	v_add_f32_e32 v7, v7, v9
	v_lshlrev_b32_e32 v8, 16, v50
	v_and_b32_e32 v9, 0xffff0000, v50
	v_add_f32_e32 v0, v0, v8
	v_add_f32_e32 v1, v1, v9
	v_lshlrev_b32_e32 v8, 16, v51
	v_and_b32_e32 v9, 0xffff0000, v51
	v_add_f32_e32 v8, v2, v8
	v_add_f32_e32 v9, v3, v9
	v_cvt_pk_bf16_f32 v2, v4, v5
	v_add_f32_e32 v12, v13, v12
	s_nop 0
	v_mul_f32_e32 v3, v5, v5
	v_fmac_f32_e32 v3, v4, v4
	v_add_f32_e32 v4, v3, v12
	v_cvt_pk_bf16_f32 v3, v6, v7
	s_nop 0
	v_and_b32_e32 v10, 0xffff0000, v3
	v_sub_f32_e32 v10, v7, v10
	s_nop 0
	v_mul_f32_e32 v5, v7, v7
	v_fmac_f32_e32 v5, v6, v6
	v_add_f32_e32 v5, v5, v4
	v_cvt_pk_bf16_f32 v4, v0, v1
	s_nop 0
	v_mul_f32_e32 v1, v1, v1
	v_fmac_f32_e32 v1, v0, v0
	v_add_f32_e32 v0, v1, v5
	v_mul_f32_e32 v1, v9, v9
	v_fmac_f32_e32 v1, v8, v8
	v_add_f32_e32 v0, v1, v0
	ds_bpermute_b32 v1, v140, v0
	s_waitcnt lgkmcnt(0)
	v_add_f32_e32 v0, v0, v1
	ds_bpermute_b32 v1, v141, v0
	v_cvt_pk_bf16_f32 v5, v8, v9
	s_nop 0
	v_lshlrev_b32_e32 v6, 16, v5
	v_sub_f32_e32 v6, v8, v6
	v_and_b32_e32 v7, 0xffff0000, v5
	v_sub_f32_e32 v7, v9, v7
	v_cvt_pk_bf16_f32 v6, v6, v7
	global_store_dwordx4 v[58:59], v[2:5], off offset:256
	s_and_saveexec_b64 s[18:19], s[2:3]
	s_cbranch_execz .LBB0_430
	s_waitcnt lgkmcnt(0)
	v_add_f32_e32 v2, v0, v1
	v_lshlrev_b64 v[0:1], 6, v[56:57]
	v_lshl_add_u64 v[0:1], s[40:41], 0, v[0:1]
	v_lshl_add_u64 v[0:1], s[16:17], 2, v[0:1]
	s_lshl_b32 s90, s35, 2
	v_lshl_add_u64 v[0:1], v[0:1], 0, s[90:91]
	global_store_dword v[0:1], v2, off

.LBB0_1068:
	s_lshl_b32 s9, s54, 8
	s_add_i32 s9, s9, s27
	v_or_b32_e32 v154, s9, v157
	v_ashrrev_i32_e32 v155, 31, v154
	v_or_b32_e32 v150, 16, v154
	v_lshlrev_b64 v[146:147], 6, v[154:155]
	v_ashrrev_i32_e32 v151, 31, v150
	v_or_b32_e32 v158, 32, v154
	v_lshl_add_u64 v[146:147], v[136:137], 0, v[146:147]
	v_lshlrev_b64 v[150:151], 6, v[150:151]
	v_ashrrev_i32_e32 v159, 31, v158
	global_load_dwordx4 v[146:149], v[146:147], off
	v_lshl_add_u64 v[150:151], v[136:137], 0, v[150:151]
	v_lshlrev_b64 v[158:159], 6, v[158:159]
	global_load_dwordx4 v[150:153], v[150:151], off
	v_lshl_add_u64 v[158:159], v[136:137], 0, v[158:159]
	global_load_dwordx4 v[178:181], v[158:159], off
	v_or_b32_e32 v158, 48, v154
	v_ashrrev_i32_e32 v159, 31, v158
	v_lshlrev_b64 v[158:159], 6, v[158:159]
	v_lshl_add_u64 v[158:159], v[136:137], 0, v[158:159]
	global_load_dwordx4 v[190:193], v[158:159], off
	v_add_u32_e32 v158, 0x80, v154
	v_ashrrev_i32_e32 v159, 31, v158
	v_lshlrev_b64 v[158:159], 6, v[158:159]
	v_lshl_add_u64 v[158:159], v[136:137], 0, v[158:159]
	global_load_dwordx4 v[194:197], v[158:159], off
	v_add_u32_e32 v158, 0x90, v154
	v_ashrrev_i32_e32 v159, 31, v158
	v_lshlrev_b64 v[158:159], 6, v[158:159]
	v_lshl_add_u64 v[158:159], v[136:137], 0, v[158:159]
	global_load_dwordx4 v[198:201], v[158:159], off
	v_add_u32_e32 v158, 0xa0, v154
	v_add_u32_e32 v154, 0xb0, v154
	v_ashrrev_i32_e32 v159, 31, v158
	v_ashrrev_i32_e32 v155, 31, v154
	v_lshlrev_b64 v[158:159], 6, v[158:159]
	v_lshlrev_b64 v[154:155], 6, v[154:155]
	v_lshl_add_u64 v[158:159], v[136:137], 0, v[158:159]
	v_lshl_add_u64 v[154:155], v[136:137], 0, v[154:155]
	global_load_dwordx4 v[202:205], v[158:159], off
	global_load_dwordx4 v[206:209], v[154:155], off
	v_and_b32_e32 v156, 64, v213
	v_xor_b32_e32 v145, 16, v213
	v_add_u32_e32 v156, 64, v156
	v_cmp_lt_i32_e32 vcc, v145, v156
	s_mov_b64 s[56:57], s[44:45]
	s_mov_b32 s55, s72
	v_cndmask_b32_e32 v145, v213, v145, vcc
	v_lshlrev_b32_e32 v165, 2, v145
	v_xor_b32_e32 v145, 32, v213
	v_cmp_lt_i32_e32 vcc, v145, v156
	s_waitcnt vmcnt(0)
	v_mov_b32_e32 v154, v147
	v_mov_b32_e32 v155, v148
	v_mov_b32_e32 v147, v149
	v_pk_add_f32 v[162:163], v[154:155], v[146:147]
	v_mov_b32_e32 v146, v151
	v_mov_b32_e32 v147, v152
	v_mov_b32_e32 v151, v153
	v_pk_add_f32 v[166:167], v[146:147], v[150:151]
	v_mov_b32_e32 v146, v179
	v_mov_b32_e32 v147, v180
	v_mov_b32_e32 v179, v181
	v_pk_add_f32 v[154:155], v[146:147], v[178:179]
	v_mov_b32_e32 v178, v166
	v_mov_b32_e32 v179, v162
	v_mov_b32_e32 v162, v167
	v_pk_add_f32 v[162:163], v[178:179], v[162:163]
	ds_bpermute_b32 v167, v165, v163
	ds_bpermute_b32 v166, v165, v162
	v_cndmask_b32_e32 v145, v213, v145, vcc
	v_lshlrev_b32_e32 v145, 2, v145
	v_mov_b32_e32 v146, v191
	v_mov_b32_e32 v147, v192
	s_waitcnt lgkmcnt(0)
	v_pk_add_f32 v[162:163], v[162:163], v[166:167]
	ds_bpermute_b32 v167, v145, v163
	ds_bpermute_b32 v166, v145, v162
	v_mov_b32_e32 v191, v193
	v_pk_add_f32 v[158:159], v[146:147], v[190:191]
	v_mov_b32_e32 v146, v195
	v_mov_b32_e32 v147, v196
	s_waitcnt lgkmcnt(0)
	v_pk_add_f32 v[166:167], v[162:163], v[166:167]
	v_mov_b64_e32 v[162:163], s[64:65]
	v_pk_fma_f32 v[166:167], v[166:167], s[28:29], v[162:163] op_sel_hi:[1,0,0]
	v_mov_b32_e32 v195, v197
	v_mul_f32_e32 v156, 0x4b800000, v167
	v_cmp_gt_f32_e64 s[0:1], s52, v167
	v_cmp_gt_f32_e32 vcc, s52, v166
	v_pk_add_f32 v[150:151], v[146:147], v[194:195]
	v_cndmask_b32_e64 v156, v167, v156, s[0:1]
	v_rsq_f32_e32 v156, v156
	v_mov_b32_e32 v146, v199
	v_mov_b32_e32 v147, v200
	v_mov_b32_e32 v199, v201
	v_mul_f32_e32 v160, 0x45800000, v156
	v_cndmask_b32_e64 v160, v156, v160, s[0:1]
	v_mul_f32_e32 v156, 0x4b800000, v166
	v_cndmask_b32_e32 v156, v166, v156, vcc
	v_rsq_f32_e32 v156, v156
	v_pk_add_f32 v[152:153], v[146:147], v[198:199]
	v_mov_b32_e32 v146, v203
	v_mov_b32_e32 v147, v204
	v_mul_f32_e32 v166, 0x45800000, v156
	v_mov_b32_e32 v203, v205
	v_mov_b32_e32 v148, v207
	v_mov_b32_e32 v149, v208
	v_mov_b32_e32 v207, v209
	v_cndmask_b32_e32 v156, v156, v166, vcc
	v_mov_b32_e32 v166, v158
	v_mov_b32_e32 v167, v154
	v_mov_b32_e32 v154, v159
	v_pk_add_f32 v[146:147], v[146:147], v[202:203]
	v_pk_add_f32 v[148:149], v[148:149], v[206:207]
	v_pk_add_f32 v[154:155], v[166:167], v[154:155]
	v_mov_b32_e32 v166, v152
	v_mov_b32_e32 v167, v150
	v_mov_b32_e32 v150, v153
	v_pk_add_f32 v[150:151], v[166:167], v[150:151]
	v_mov_b32_e32 v166, v148
	v_mov_b32_e32 v167, v146
	v_mov_b32_e32 v146, v149
	v_pk_add_f32 v[146:147], v[166:167], v[146:147]
	ds_bpermute_b32 v159, v165, v155
	ds_bpermute_b32 v158, v165, v154
	ds_bpermute_b32 v153, v165, v151
	ds_bpermute_b32 v152, v165, v150
	ds_bpermute_b32 v149, v165, v147
	ds_bpermute_b32 v148, v165, v146
	s_waitcnt lgkmcnt(4)
	v_pk_add_f32 v[154:155], v[154:155], v[158:159]
	ds_bpermute_b32 v159, v145, v155
	s_waitcnt lgkmcnt(3)
	v_pk_add_f32 v[150:151], v[150:151], v[152:153]
	ds_bpermute_b32 v158, v145, v154
	s_waitcnt lgkmcnt(2)
	v_pk_add_f32 v[146:147], v[146:147], v[148:149]
	ds_bpermute_b32 v153, v145, v151
	ds_bpermute_b32 v152, v145, v150
	ds_bpermute_b32 v149, v145, v147
	ds_bpermute_b32 v148, v145, v146
	s_waitcnt lgkmcnt(4)
	v_pk_add_f32 v[154:155], v[154:155], v[158:159]
	s_waitcnt lgkmcnt(2)
	v_pk_add_f32 v[150:151], v[150:151], v[152:153]
	v_pk_fma_f32 v[154:155], v[154:155], s[28:29], v[162:163] op_sel_hi:[1,0,0]
	s_waitcnt lgkmcnt(0)
	v_pk_add_f32 v[146:147], v[146:147], v[148:149]
	v_pk_fma_f32 v[150:151], v[150:151], s[28:29], v[162:163] op_sel_hi:[1,0,0]
	v_pk_fma_f32 v[146:147], v[146:147], s[28:29], v[162:163] op_sel_hi:[1,0,0]
	v_mul_f32_e32 v158, 0x4b800000, v155
	v_cmp_gt_f32_e64 s[0:1], s52, v155
	v_mul_f32_e32 v152, 0x4b800000, v151
	s_nop 0
	v_cndmask_b32_e64 v155, v155, v158, s[0:1]
	v_rsq_f32_e32 v155, v155
	v_mul_f32_e32 v145, 0x4b800000, v147
	v_mul_f32_e32 v158, 0x45800000, v155
	v_cndmask_b32_e64 v158, v155, v158, s[0:1]
	v_cmp_gt_f32_e64 s[0:1], s52, v151
	v_cmp_gt_f32_e32 vcc, s52, v154
	s_nop 0
	v_cndmask_b32_e64 v151, v151, v152, s[0:1]
	v_rsq_f32_e32 v151, v151
	v_mul_f32_e32 v155, 0x4b800000, v154
	v_mul_f32_e32 v152, 0x45800000, v151
	v_cndmask_b32_e64 v152, v151, v152, s[0:1]
	v_cmp_gt_f32_e64 s[0:1], s52, v147
	s_nop 1
	v_cndmask_b32_e64 v145, v147, v145, s[0:1]
	v_rsq_f32_e32 v145, v145
	v_cndmask_b32_e32 v154, v154, v155, vcc
	v_mul_f32_e32 v236, 0xbfb8aa3b, v160
	v_mul_f32_e32 v237, v160, v160
	v_rcp_f32_e32 v237, v237
	v_mul_f32_e32 v220, v236, v124
	v_mul_f32_e32 v222, v236, v125
	v_mul_f32_e32 v224, v236, v126
	v_mul_f32_e32 v226, v236, v127
	v_mul_f32_e32 v221, v124, v120
	v_mul_f32_e32 v223, v125, v121
	v_mul_f32_e32 v225, v126, v122
	v_mul_f32_e32 v227, v127, v123
	v_exp_f32_e32 v220, v220
	v_exp_f32_e32 v222, v222
	v_exp_f32_e32 v224, v224
	v_exp_f32_e32 v226, v226
	v_fma_f32 v220, v220, v237, v237
	v_fma_f32 v222, v222, v237, v237
	v_fma_f32 v224, v224, v237, v237
	v_fma_f32 v226, v226, v237, v237
	v_rcp_f32_e32 v220, v220
	v_rcp_f32_e32 v222, v222
	v_rcp_f32_e32 v224, v224
	v_rcp_f32_e32 v226, v226
	v_mul_f32_e32 v124, v221, v220
	v_mul_f32_e32 v125, v223, v222
	v_mul_f32_e32 v126, v225, v224
	v_mul_f32_e32 v122, v227, v226
	v_mul_f32_e32 v147, 0x45800000, v145
	v_cndmask_b32_e64 v148, v145, v147, s[0:1]
	s_lshl_b32 s0, s36, 7
	s_or_b32 s0, s0, s34
	s_ashr_i32 s11, s0, 6
	s_ashr_i32 s0, s9, 8
	s_mul_i32 s0, s0, 44
	s_add_i32 s0, s0, s11
	s_lshl_b32 s0, s0, 1
	s_or_b32 s0, s0, s87
	s_ashr_i32 s1, s0, 31
	s_lshl_b64 s[0:1], s[0:1], 14
	v_rsq_f32_e32 v154, v154
	s_nop 0
	v_mul_f32_e32 v155, 0x45800000, v154
	v_cndmask_b32_e32 v154, v154, v155, vcc
	v_cmp_gt_f32_e32 vcc, s52, v150
	v_mul_f32_e32 v151, 0x4b800000, v150
	s_nop 0
	v_cndmask_b32_e32 v150, v150, v151, vcc
	v_rsq_f32_e32 v150, v150
	s_addk_i32 s9, 0x80
	v_mul_f32_e32 v151, 0x45800000, v150
	v_cndmask_b32_e32 v150, v150, v151, vcc
	v_cmp_gt_f32_e32 vcc, s52, v146
	v_mul_f32_e32 v145, 0x4b800000, v146
	s_nop 0
	v_cndmask_b32_e32 v145, v146, v145, vcc
	v_rsq_f32_e32 v145, v145
	v_mul_f32_e32 v228, v236, v116
	v_mul_f32_e32 v230, v236, v117
	v_mul_f32_e32 v232, v236, v118
	v_mul_f32_e32 v234, v236, v119
	v_mul_f32_e32 v229, v116, v112
	v_mul_f32_e32 v231, v117, v113
	v_mul_f32_e32 v233, v118, v114
	v_mul_f32_e32 v235, v119, v115
	v_exp_f32_e32 v228, v228
	v_exp_f32_e32 v230, v230
	v_exp_f32_e32 v232, v232
	v_exp_f32_e32 v234, v234
	v_fma_f32 v228, v228, v237, v237
	v_fma_f32 v230, v230, v237, v237
	v_fma_f32 v232, v232, v237, v237
	v_fma_f32 v234, v234, v237, v237
	v_rcp_f32_e32 v228, v228
	v_rcp_f32_e32 v230, v230
	v_rcp_f32_e32 v232, v232
	v_rcp_f32_e32 v234, v234
	v_mul_f32_e32 v116, v229, v228
	v_mul_f32_e32 v117, v231, v230
	v_mul_f32_e32 v118, v233, v232
	v_mul_f32_e32 v112, v235, v234
	v_cvt_pk_bf16_f32 v114, v124, v125
	v_cvt_pk_bf16_f32 v115, v126, v122
	v_cvt_pk_bf16_f32 v116, v116, v117
	v_mul_f32_e32 v146, 0x45800000, v145
	v_cndmask_b32_e32 v146, v145, v146, vcc
	v_mov_b32_e32 v145, v169
	v_cvt_pk_bf16_f32 v117, v118, v112
	v_lshl_add_u64 v[112:113], v[138:139], 0, s[0:1]
	global_store_dwordx4 v[112:113], v[114:117], off
	s_ashr_i32 s0, s9, 8
	s_mul_i32 s0, s0, 44
	s_add_i32 s0, s0, s11
	s_lshl_b32 s0, s0, 1
	s_or_b32 s0, s0, s87
	s_ashr_i32 s1, s0, 31
	s_and_b32 s9, s9, 0xc0
	s_lshl_b64 s[0:1], s[0:1], 14
	s_add_u32 s0, s48, s0
	s_addc_u32 s1, s49, s1
	s_andn2_b64 vcc, exec, s[2:3]
	v_mul_f32_e32 v238, 0xbfb8aa3b, v156
	v_mul_f32_e32 v239, v156, v156
	v_rcp_f32_e32 v239, v239
	v_mul_f32_e32 v220, v238, v108
	v_mul_f32_e32 v222, v238, v109
	v_mul_f32_e32 v224, v238, v110
	v_mul_f32_e32 v226, v238, v111
	v_mul_f32_e32 v221, v108, v104
	v_mul_f32_e32 v223, v109, v105
	v_mul_f32_e32 v225, v110, v106
	v_mul_f32_e32 v227, v111, v107
	v_exp_f32_e32 v220, v220
	v_exp_f32_e32 v222, v222
	v_exp_f32_e32 v224, v224
	v_exp_f32_e32 v226, v226
	v_fma_f32 v220, v220, v239, v239
	v_fma_f32 v222, v222, v239, v239
	v_fma_f32 v224, v224, v239, v239
	v_fma_f32 v226, v226, v239, v239
	v_rcp_f32_e32 v220, v220
	v_rcp_f32_e32 v222, v222
	v_rcp_f32_e32 v224, v224
	v_rcp_f32_e32 v226, v226
	v_mul_f32_e32 v108, v221, v220
	v_mul_f32_e32 v109, v223, v222
	v_mul_f32_e32 v110, v225, v224
	v_mul_f32_e32 v106, v227, v226
	v_mul_f32_e32 v228, v238, v100
	v_mul_f32_e32 v230, v238, v101
	v_mul_f32_e32 v232, v238, v102
	v_mul_f32_e32 v234, v238, v103
	v_mul_f32_e32 v229, v100, v96
	v_mul_f32_e32 v231, v101, v97
	v_mul_f32_e32 v233, v102, v98
	v_mul_f32_e32 v235, v103, v99
	v_exp_f32_e32 v228, v228
	v_exp_f32_e32 v230, v230
	v_exp_f32_e32 v232, v232
	v_exp_f32_e32 v234, v234
	v_fma_f32 v228, v228, v239, v239
	v_fma_f32 v230, v230, v239, v239
	v_fma_f32 v232, v232, v239, v239
	v_fma_f32 v234, v234, v239, v239
	v_rcp_f32_e32 v228, v228
	v_rcp_f32_e32 v230, v230
	v_rcp_f32_e32 v232, v232
	v_rcp_f32_e32 v234, v234
	v_mul_f32_e32 v100, v229, v228
	v_mul_f32_e32 v101, v231, v230
	v_mul_f32_e32 v102, v233, v232
	v_mul_f32_e32 v99, v235, v234
	v_cvt_pk_bf16_f32 v96, v108, v109
	v_cvt_pk_bf16_f32 v97, v110, v106
	v_cvt_pk_bf16_f32 v98, v100, v101
	v_cvt_pk_bf16_f32 v99, v102, v99
	global_store_dwordx4 v[112:113], v[96:99], off offset:1024
	s_nop 1
	v_mul_f32_e32 v240, 0xbfb8aa3b, v158
	v_mul_f32_e32 v241, v158, v158
	v_rcp_f32_e32 v241, v241
	v_mul_f32_e32 v220, v240, v92
	v_mul_f32_e32 v222, v240, v93
	v_mul_f32_e32 v224, v240, v94
	v_mul_f32_e32 v226, v240, v95
	v_mul_f32_e32 v221, v92, v88
	v_mul_f32_e32 v223, v93, v89
	v_mul_f32_e32 v225, v94, v90
	v_mul_f32_e32 v227, v95, v91
	v_exp_f32_e32 v220, v220
	v_exp_f32_e32 v222, v222
	v_exp_f32_e32 v224, v224
	v_exp_f32_e32 v226, v226
	v_fma_f32 v220, v220, v241, v241
	v_fma_f32 v222, v222, v241, v241
	v_fma_f32 v224, v224, v241, v241
	v_fma_f32 v226, v226, v241, v241
	v_rcp_f32_e32 v220, v220
	v_rcp_f32_e32 v222, v222
	v_rcp_f32_e32 v224, v224
	v_rcp_f32_e32 v226, v226
	v_mul_f32_e32 v92, v221, v220
	v_mul_f32_e32 v93, v223, v222
	v_mul_f32_e32 v94, v225, v224
	v_mul_f32_e32 v90, v227, v226
	v_mul_f32_e32 v228, v240, v84
	v_mul_f32_e32 v230, v240, v85
	v_mul_f32_e32 v232, v240, v86
	v_mul_f32_e32 v234, v240, v87
	v_mul_f32_e32 v229, v84, v80
	v_mul_f32_e32 v231, v85, v81
	v_mul_f32_e32 v233, v86, v82
	v_mul_f32_e32 v235, v87, v83
	v_exp_f32_e32 v228, v228
	v_exp_f32_e32 v230, v230
	v_exp_f32_e32 v232, v232
	v_exp_f32_e32 v234, v234
	v_fma_f32 v228, v228, v241, v241
	v_fma_f32 v230, v230, v241, v241
	v_fma_f32 v232, v232, v241, v241
	v_fma_f32 v234, v234, v241, v241
	v_rcp_f32_e32 v228, v228
	v_rcp_f32_e32 v230, v230
	v_rcp_f32_e32 v232, v232
	v_rcp_f32_e32 v234, v234
	v_mul_f32_e32 v84, v229, v228
	v_mul_f32_e32 v85, v231, v230
	v_mul_f32_e32 v86, v233, v232
	v_mul_f32_e32 v83, v235, v234
	v_cvt_pk_bf16_f32 v80, v92, v93
	v_cvt_pk_bf16_f32 v81, v94, v90
	v_cvt_pk_bf16_f32 v82, v84, v85
	v_cvt_pk_bf16_f32 v83, v86, v83
	global_store_dwordx4 v[112:113], v[80:83], off offset:2048
	s_nop 1
	v_mul_f32_e32 v242, 0xbfb8aa3b, v154
	v_mul_f32_e32 v243, v154, v154
	v_rcp_f32_e32 v243, v243
	v_mul_f32_e32 v220, v242, v76
	v_mul_f32_e32 v222, v242, v77
	v_mul_f32_e32 v224, v242, v78
	v_mul_f32_e32 v226, v242, v79
	v_mul_f32_e32 v221, v76, v72
	v_mul_f32_e32 v223, v77, v73
	v_mul_f32_e32 v225, v78, v74
	v_mul_f32_e32 v227, v79, v75
	v_exp_f32_e32 v220, v220
	v_exp_f32_e32 v222, v222
	v_exp_f32_e32 v224, v224
	v_exp_f32_e32 v226, v226
	v_fma_f32 v220, v220, v243, v243
	v_fma_f32 v222, v222, v243, v243
	v_fma_f32 v224, v224, v243, v243
	v_fma_f32 v226, v226, v243, v243
	v_rcp_f32_e32 v220, v220
	v_rcp_f32_e32 v222, v222
	v_rcp_f32_e32 v224, v224
	v_rcp_f32_e32 v226, v226
	v_mul_f32_e32 v76, v221, v220
	v_mul_f32_e32 v77, v223, v222
	v_mul_f32_e32 v78, v225, v224
	v_mul_f32_e32 v74, v227, v226
	v_mul_f32_e32 v228, v242, v68
	v_mul_f32_e32 v230, v242, v69
	v_mul_f32_e32 v232, v242, v70
	v_mul_f32_e32 v234, v242, v71
	v_mul_f32_e32 v229, v68, v64
	v_mul_f32_e32 v231, v69, v65
	v_mul_f32_e32 v233, v70, v66
	v_mul_f32_e32 v235, v71, v67
	v_exp_f32_e32 v228, v228
	v_exp_f32_e32 v230, v230
	v_exp_f32_e32 v232, v232
	v_exp_f32_e32 v234, v234
	v_fma_f32 v228, v228, v243, v243
	v_fma_f32 v230, v230, v243, v243
	v_fma_f32 v232, v232, v243, v243
	v_fma_f32 v234, v234, v243, v243
	v_rcp_f32_e32 v228, v228
	v_rcp_f32_e32 v230, v230
	v_rcp_f32_e32 v232, v232
	v_rcp_f32_e32 v234, v234
	v_mul_f32_e32 v68, v229, v228
	v_mul_f32_e32 v69, v231, v230
	v_mul_f32_e32 v70, v233, v232
	v_mul_f32_e32 v67, v235, v234
	v_cvt_pk_bf16_f32 v64, v76, v77
	v_cvt_pk_bf16_f32 v65, v78, v74
	v_cvt_pk_bf16_f32 v66, v68, v69
	v_cvt_pk_bf16_f32 v67, v70, v67
	global_store_dwordx4 v[112:113], v[64:67], off offset:3072
	s_nop 1
	v_or_b32_e32 v66, s9, v157
	v_lshlrev_b32_e32 v168, 6, v66
	v_mul_f32_e32 v244, 0xbfb8aa3b, v152
	v_mul_f32_e32 v245, v152, v152
	v_rcp_f32_e32 v245, v245
	v_mul_f32_e32 v220, v244, v60
	v_mul_f32_e32 v222, v244, v61
	v_mul_f32_e32 v224, v244, v62
	v_mul_f32_e32 v226, v244, v63
	v_mul_f32_e32 v221, v60, v56
	v_mul_f32_e32 v223, v61, v57
	v_mul_f32_e32 v225, v62, v58
	v_mul_f32_e32 v227, v63, v59
	v_exp_f32_e32 v220, v220
	v_exp_f32_e32 v222, v222
	v_exp_f32_e32 v224, v224
	v_exp_f32_e32 v226, v226
	v_fma_f32 v220, v220, v245, v245
	v_fma_f32 v222, v222, v245, v245
	v_fma_f32 v224, v224, v245, v245
	v_fma_f32 v226, v226, v245, v245
	v_rcp_f32_e32 v220, v220
	v_rcp_f32_e32 v222, v222
	v_rcp_f32_e32 v224, v224
	v_rcp_f32_e32 v226, v226
	v_mul_f32_e32 v60, v221, v220
	v_mul_f32_e32 v61, v223, v222
	v_mul_f32_e32 v62, v225, v224
	v_mul_f32_e32 v58, v227, v226
	v_mul_f32_e32 v228, v244, v52
	v_mul_f32_e32 v230, v244, v53
	v_mul_f32_e32 v232, v244, v54
	v_mul_f32_e32 v234, v244, v55
	v_mul_f32_e32 v229, v52, v48
	v_mul_f32_e32 v231, v53, v49
	v_mul_f32_e32 v233, v54, v50
	v_mul_f32_e32 v235, v55, v51
	v_exp_f32_e32 v228, v228
	v_exp_f32_e32 v230, v230
	v_exp_f32_e32 v232, v232
	v_exp_f32_e32 v234, v234
	v_fma_f32 v228, v228, v245, v245
	v_fma_f32 v230, v230, v245, v245
	v_fma_f32 v232, v232, v245, v245
	v_fma_f32 v234, v234, v245, v245
	v_rcp_f32_e32 v228, v228
	v_rcp_f32_e32 v230, v230
	v_rcp_f32_e32 v232, v232
	v_rcp_f32_e32 v234, v234
	v_mul_f32_e32 v52, v229, v228
	v_mul_f32_e32 v53, v231, v230
	v_mul_f32_e32 v54, v233, v232
	v_mul_f32_e32 v48, v235, v234
	v_cvt_pk_bf16_f32 v50, v60, v61
	v_cvt_pk_bf16_f32 v51, v62, v58
	v_cvt_pk_bf16_f32 v52, v52, v53
	s_nop 0
	v_cvt_pk_bf16_f32 v53, v54, v48
	v_lshl_add_u64 v[48:49], s[0:1], 0, v[168:169]
	v_lshl_add_u64 v[48:49], v[48:49], 0, v[144:145]
	global_store_dwordx4 v[48:49], v[50:53], off
	s_mov_b64 s[0:1], -1
	v_mul_f32_e32 v246, 0xbfb8aa3b, v150
	v_mul_f32_e32 v247, v150, v150
	v_rcp_f32_e32 v247, v247
	v_mul_f32_e32 v220, v246, v44
	v_mul_f32_e32 v222, v246, v45
	v_mul_f32_e32 v224, v246, v46
	v_mul_f32_e32 v226, v246, v47
	v_mul_f32_e32 v221, v44, v40
	v_mul_f32_e32 v223, v45, v41
	v_mul_f32_e32 v225, v46, v42
	v_mul_f32_e32 v227, v47, v43
	v_exp_f32_e32 v220, v220
	v_exp_f32_e32 v222, v222
	v_exp_f32_e32 v224, v224
	v_exp_f32_e32 v226, v226
	v_fma_f32 v220, v220, v247, v247
	v_fma_f32 v222, v222, v247, v247
	v_fma_f32 v224, v224, v247, v247
	v_fma_f32 v226, v226, v247, v247
	v_rcp_f32_e32 v220, v220
	v_rcp_f32_e32 v222, v222
	v_rcp_f32_e32 v224, v224
	v_rcp_f32_e32 v226, v226
	v_mul_f32_e32 v44, v221, v220
	v_mul_f32_e32 v45, v223, v222
	v_mul_f32_e32 v46, v225, v224
	v_mul_f32_e32 v42, v227, v226
	v_mul_f32_e32 v228, v246, v36
	v_mul_f32_e32 v230, v246, v37
	v_mul_f32_e32 v232, v246, v38
	v_mul_f32_e32 v234, v246, v39
	v_mul_f32_e32 v229, v36, v32
	v_mul_f32_e32 v231, v37, v33
	v_mul_f32_e32 v233, v38, v34
	v_mul_f32_e32 v235, v39, v35
	v_exp_f32_e32 v228, v228
	v_exp_f32_e32 v230, v230
	v_exp_f32_e32 v232, v232
	v_exp_f32_e32 v234, v234
	v_fma_f32 v228, v228, v247, v247
	v_fma_f32 v230, v230, v247, v247
	v_fma_f32 v232, v232, v247, v247
	v_fma_f32 v234, v234, v247, v247
	v_rcp_f32_e32 v228, v228
	v_rcp_f32_e32 v230, v230
	v_rcp_f32_e32 v232, v232
	v_rcp_f32_e32 v234, v234
	v_mul_f32_e32 v36, v229, v228
	v_mul_f32_e32 v37, v231, v230
	v_mul_f32_e32 v38, v233, v232
	v_mul_f32_e32 v35, v235, v234
	v_cvt_pk_bf16_f32 v32, v44, v45
	v_cvt_pk_bf16_f32 v33, v46, v42
	v_cvt_pk_bf16_f32 v34, v36, v37
	v_cvt_pk_bf16_f32 v35, v38, v35
	global_store_dwordx4 v[48:49], v[32:35], off offset:1024
	s_nop 1
	v_mul_f32_e32 v248, 0xbfb8aa3b, v148
	v_mul_f32_e32 v249, v148, v148
	v_rcp_f32_e32 v249, v249
	v_mul_f32_e32 v220, v248, v28
	v_mul_f32_e32 v222, v248, v29
	v_mul_f32_e32 v224, v248, v30
	v_mul_f32_e32 v226, v248, v31
	v_mul_f32_e32 v221, v28, v24
	v_mul_f32_e32 v223, v29, v25
	v_mul_f32_e32 v225, v30, v26
	v_mul_f32_e32 v227, v31, v27
	v_exp_f32_e32 v220, v220
	v_exp_f32_e32 v222, v222
	v_exp_f32_e32 v224, v224
	v_exp_f32_e32 v226, v226
	v_fma_f32 v220, v220, v249, v249
	v_fma_f32 v222, v222, v249, v249
	v_fma_f32 v224, v224, v249, v249
	v_fma_f32 v226, v226, v249, v249
	v_rcp_f32_e32 v220, v220
	v_rcp_f32_e32 v222, v222
	v_rcp_f32_e32 v224, v224
	v_rcp_f32_e32 v226, v226
	v_mul_f32_e32 v28, v221, v220
	v_mul_f32_e32 v29, v223, v222
	v_mul_f32_e32 v30, v225, v224
	v_mul_f32_e32 v26, v227, v226
	v_mul_f32_e32 v228, v248, v20
	v_mul_f32_e32 v230, v248, v21
	v_mul_f32_e32 v232, v248, v22
	v_mul_f32_e32 v234, v248, v23
	v_mul_f32_e32 v229, v20, v16
	v_mul_f32_e32 v231, v21, v17
	v_mul_f32_e32 v233, v22, v18
	v_mul_f32_e32 v235, v23, v19
	v_exp_f32_e32 v228, v228
	v_exp_f32_e32 v230, v230
	v_exp_f32_e32 v232, v232
	v_exp_f32_e32 v234, v234
	v_fma_f32 v228, v228, v249, v249
	v_fma_f32 v230, v230, v249, v249
	v_fma_f32 v232, v232, v249, v249
	v_fma_f32 v234, v234, v249, v249
	v_rcp_f32_e32 v228, v228
	v_rcp_f32_e32 v230, v230
	v_rcp_f32_e32 v232, v232
	v_rcp_f32_e32 v234, v234
	v_mul_f32_e32 v20, v229, v228
	v_mul_f32_e32 v21, v231, v230
	v_mul_f32_e32 v22, v233, v232
	v_mul_f32_e32 v19, v235, v234
	v_cvt_pk_bf16_f32 v16, v28, v29
	v_cvt_pk_bf16_f32 v17, v30, v26
	v_cvt_pk_bf16_f32 v18, v20, v21
	v_cvt_pk_bf16_f32 v19, v22, v19
	global_store_dwordx4 v[48:49], v[16:19], off offset:2048
	s_nop 1
	v_mul_f32_e32 v250, 0xbfb8aa3b, v146
	v_mul_f32_e32 v251, v146, v146
	v_rcp_f32_e32 v251, v251
	v_mul_f32_e32 v220, v250, v12
	v_mul_f32_e32 v222, v250, v13
	v_mul_f32_e32 v224, v250, v14
	v_mul_f32_e32 v226, v250, v15
	v_mul_f32_e32 v221, v12, v8
	v_mul_f32_e32 v223, v13, v9
	v_mul_f32_e32 v225, v14, v10
	v_mul_f32_e32 v227, v15, v11
	v_exp_f32_e32 v220, v220
	v_exp_f32_e32 v222, v222
	v_exp_f32_e32 v224, v224
	v_exp_f32_e32 v226, v226
	v_fma_f32 v220, v220, v251, v251
	v_fma_f32 v222, v222, v251, v251
	v_fma_f32 v224, v224, v251, v251
	v_fma_f32 v226, v226, v251, v251
	v_rcp_f32_e32 v220, v220
	v_rcp_f32_e32 v222, v222
	v_rcp_f32_e32 v224, v224
	v_rcp_f32_e32 v226, v226
	v_mul_f32_e32 v12, v221, v220
	v_mul_f32_e32 v13, v223, v222
	v_mul_f32_e32 v14, v225, v224
	v_mul_f32_e32 v10, v227, v226
	v_mul_f32_e32 v228, v250, v4
	v_mul_f32_e32 v230, v250, v5
	v_mul_f32_e32 v232, v250, v6
	v_mul_f32_e32 v234, v250, v7
	v_mul_f32_e32 v229, v4, v0
	v_mul_f32_e32 v231, v5, v1
	v_mul_f32_e32 v233, v6, v2
	v_mul_f32_e32 v235, v7, v3
	v_exp_f32_e32 v228, v228
	v_exp_f32_e32 v230, v230
	v_exp_f32_e32 v232, v232
	v_exp_f32_e32 v234, v234
	v_fma_f32 v228, v228, v251, v251
	v_fma_f32 v230, v230, v251, v251
	v_fma_f32 v232, v232, v251, v251
	v_fma_f32 v234, v234, v251, v251
	v_rcp_f32_e32 v228, v228
	v_rcp_f32_e32 v230, v230
	v_rcp_f32_e32 v232, v232
	v_rcp_f32_e32 v234, v234
	v_mul_f32_e32 v4, v229, v228
	v_mul_f32_e32 v5, v231, v230
	v_mul_f32_e32 v6, v233, v232
	v_mul_f32_e32 v3, v235, v234
	v_cvt_pk_bf16_f32 v0, v12, v13
	v_cvt_pk_bf16_f32 v1, v14, v10
	v_cvt_pk_bf16_f32 v2, v4, v5
	v_cvt_pk_bf16_f32 v3, v6, v3
	global_store_dwordx4 v[48:49], v[0:3], off offset:3072
	s_cbranch_vccnz .LBB0_1061
	s_andn2_b64 vcc, exec, s[4:5]
	s_cbranch_vccnz .LBB0_1060
	s_barrier
	s_branch .LBB0_1060

.LBB0_1072:
	s_nop 0
	s_nop 0
	s_nop 0
	s_nop 0
	s_nop 0
	s_nop 0
	s_nop 0
	s_nop 0
	s_nop 0
	s_nop 0
	s_nop 0
	s_nop 0
	s_nop 0
	s_nop 0
	s_nop 0
	s_nop 0
	s_nop 0
	s_nop 0
	s_nop 0
	s_nop 0
	s_nop 0
	s_nop 0
	s_nop 0
	s_nop 0
	s_nop 0
	s_nop 0
	s_nop 0
	s_nop 0
	s_nop 0
	s_nop 0
	s_nop 0
	s_nop 0
	s_nop 0
	s_nop 0
	s_nop 0
	s_nop 0
	s_nop 0
	s_nop 0
	s_nop 0
	s_nop 0
	s_nop 0
	s_nop 0
	s_nop 0
	s_nop 0
	s_nop 0
	s_nop 0
	s_nop 0
	s_nop 0
	s_nop 0
	s_nop 0
	s_nop 0
	s_nop 0
	s_nop 0
	s_nop 0
	s_nop 0
	s_nop 0
	s_nop 0
	s_nop 0
	s_nop 0
	s_nop 0
	s_nop 0
	s_nop 0
	s_nop 0
	s_nop 0
	s_nop 0
	s_nop 0
	s_nop 0
	s_nop 0
	s_nop 0
	s_nop 0
	s_nop 0
	s_nop 0
	s_nop 0
	s_nop 0
	s_nop 0
	s_nop 0
	s_nop 0
	s_nop 0
	s_nop 0
	s_nop 0
	s_nop 0
	s_nop 0
	s_nop 0
	s_nop 0
	s_nop 0
	s_nop 0
	s_nop 0
	s_nop 0
	s_nop 0
	s_nop 0
	s_nop 0
	s_nop 0
	s_nop 0
	s_nop 0
	s_nop 0
	s_getreg_b32 s2, hwreg(HW_REG_XCC_ID, 0, 4)
	s_waitcnt vmcnt(0)
	s_barrier
	s_mov_b64 s[0:1], exec
	v_readlane_b32 s4, v252, 8
	v_readlane_b32 s5, v252, 9
	s_and_b64 s[4:5], s[0:1], s[4:5]
	s_mov_b64 exec, s[4:5]
	s_cbranch_execz .LBB0_1124
	v_readlane_b32 s3, v254, 55
	s_waitcnt vmcnt(0) expcnt(0) lgkmcnt(0)
	s_and_b32 s8, s2, 15
	v_mov_b32_e32 v0, s3
	ds_read_b32 v2, v0
	v_readlane_b32 s3, v254, 56
	s_waitcnt lgkmcnt(0)
	v_cmp_ne_u32_e32 vcc, 0, v2
	v_mov_b32_e32 v0, s3
	ds_read_b32 v0, v0
	s_cbranch_vccnz .LBB0_1088
	s_mov_b32 s9, 1
	s_branch .LBB0_1076

.LBB0_1144:
	v_lshl_add_u32 v166, s57, 8, v170
	v_lshl_or_b32 v158, s56, 8, v197
	v_ashrrev_i32_e32 v167, 31, v166
	v_lshlrev_b64 v[120:121], 11, v[166:167]
	v_ashrrev_i32_e32 v159, 31, v158
	v_lshl_add_u64 v[160:161], s[42:43], 0, v[120:121]
	v_lshlrev_b64 v[120:121], 1, v[158:159]
	v_lshl_add_u64 v[194:195], v[160:161], 0, v[120:121]
	global_load_dwordx4 v[178:181], v[194:195], off
	global_load_dwordx4 v[144:147], v[194:195], off offset:256
	v_or_b32_e32 v190, 16, v166
	v_ashrrev_i32_e32 v191, 31, v190
	v_lshlrev_b64 v[122:123], 11, v[190:191]
	v_or_b32_e32 v162, 32, v166
	v_lshl_add_u64 v[122:123], s[42:43], 0, v[122:123]
	v_ashrrev_i32_e32 v163, 31, v162
	v_lshl_add_u64 v[192:193], v[122:123], 0, v[120:121]
	v_lshlrev_b64 v[122:123], 11, v[162:163]
	v_lshl_add_u64 v[122:123], s[42:43], 0, v[122:123]
	v_lshl_add_u64 v[164:165], v[122:123], 0, v[120:121]
	global_load_dwordx4 v[140:143], v[192:193], off
	global_load_dwordx4 v[128:131], v[192:193], off offset:256
	global_load_dwordx4 v[124:127], v[164:165], off
	global_load_dwordx4 v[120:123], v[164:165], off offset:256
	s_lshl_b32 s12, s56, 2
	s_ashr_i32 s13, s12, 31
	s_waitcnt vmcnt(0)
	v_lshlrev_b32_e32 v199, 16, v178
	v_and_b32_e32 v178, 0xffff0000, v178
	v_add_f32_e32 v137, v137, v178
	v_lshlrev_b32_e32 v178, 16, v179
	v_and_b32_e32 v179, 0xffff0000, v179
	v_add_f32_e32 v138, v138, v178
	v_add_f32_e32 v139, v139, v179
	v_lshlrev_b32_e32 v178, 16, v180
	v_and_b32_e32 v179, 0xffff0000, v180
	v_add_f32_e32 v178, v132, v178
	v_add_f32_e32 v179, v133, v179
	v_lshlrev_b32_e32 v132, 16, v181
	v_and_b32_e32 v133, 0xffff0000, v181
	v_add_f32_e32 v136, v136, v199
	v_add_f32_e32 v180, v134, v132
	v_add_f32_e32 v181, v135, v133
	v_cvt_pk_bf16_f32 v132, v136, v137
	s_nop 0
	v_mul_f32_e32 v134, v137, v137
	v_cvt_pk_bf16_f32 v133, v138, v139
	v_fmac_f32_e32 v134, v136, v136
	s_nop 0
	v_mul_f32_e32 v135, v139, v139
	v_fmac_f32_e32 v135, v138, v138
	v_add_f32_e32 v135, v134, v135
	v_cvt_pk_bf16_f32 v134, v178, v179
	s_nop 0
	s_nop 0
	v_mul_f32_e32 v136, v179, v179
	v_fmac_f32_e32 v136, v178, v178
	v_add_f32_e32 v136, v136, v135
	v_cvt_pk_bf16_f32 v135, v180, v181
	s_nop 0
	global_store_dwordx4 v[194:195], v[132:135], off
	v_mul_f32_e32 v137, v181, v181
	v_fmac_f32_e32 v137, v180, v180
	v_lshlrev_b32_e32 v132, 16, v144
	v_and_b32_e32 v133, 0xffff0000, v144
	v_add_f32_e32 v116, v116, v132
	v_add_f32_e32 v117, v117, v133
	v_lshlrev_b32_e32 v132, 16, v145
	v_and_b32_e32 v133, 0xffff0000, v145
	v_add_f32_e32 v118, v118, v132
	v_add_f32_e32 v119, v119, v133
	v_lshlrev_b32_e32 v132, 16, v146
	v_and_b32_e32 v133, 0xffff0000, v146
	v_add_f32_e32 v132, v112, v132
	v_add_f32_e32 v133, v113, v133
	v_lshlrev_b32_e32 v112, 16, v147
	v_and_b32_e32 v113, 0xffff0000, v147
	v_add_f32_e32 v134, v114, v112
	v_add_f32_e32 v135, v115, v113
	v_cvt_pk_bf16_f32 v112, v116, v117
	v_add_f32_e32 v136, v137, v136
	s_nop 0
	v_mul_f32_e32 v113, v117, v117
	v_fmac_f32_e32 v113, v116, v116
	v_add_f32_e32 v114, v113, v136
	v_cvt_pk_bf16_f32 v113, v118, v119
	s_nop 0
	s_nop 0
	v_mul_f32_e32 v115, v119, v119
	v_fmac_f32_e32 v115, v118, v118
	v_add_f32_e32 v115, v115, v114
	v_cvt_pk_bf16_f32 v114, v132, v133
	s_nop 0
	s_nop 0
	v_mul_f32_e32 v116, v133, v133
	v_fmac_f32_e32 v116, v132, v132
	v_add_f32_e32 v116, v116, v115
	v_cvt_pk_bf16_f32 v115, v134, v135
	s_nop 0
	global_store_dwordx4 v[194:195], v[112:115], off offset:256
	v_mul_f32_e32 v117, v135, v135
	v_fmac_f32_e32 v117, v134, v134
	v_and_b32_e32 v113, 64, v213
	v_xor_b32_e32 v112, 16, v213
	v_add_u32_e32 v113, 64, v113
	v_cmp_lt_i32_e32 vcc, v112, v113
	v_add_f32_e32 v116, v117, v116
	v_xor_b32_e32 v114, 32, v213
	v_cndmask_b32_e32 v112, v213, v112, vcc
	v_lshlrev_b32_e32 v136, 2, v112
	ds_bpermute_b32 v112, v136, v116
	v_cmp_lt_i32_e32 vcc, v114, v113
	s_waitcnt lgkmcnt(0)
	v_add_f32_e32 v112, v116, v112
	v_cndmask_b32_e32 v113, v213, v114, vcc
	v_lshlrev_b32_e32 v137, 2, v113
	ds_bpermute_b32 v113, v137, v112
	s_and_saveexec_b64 s[14:15], s[2:3]
	s_cbranch_execz .LBB0_1146
	s_waitcnt lgkmcnt(0)
	v_add_f32_e32 v114, v112, v113
	v_lshlrev_b64 v[112:113], 6, v[166:167]
	v_lshl_add_u64 v[112:113], s[40:41], 0, v[112:113]
	v_lshl_add_u64 v[112:113], s[12:13], 2, v[112:113]
	s_lshl_b32 s90, s35, 2
	v_lshl_add_u64 v[112:113], v[112:113], 0, s[90:91]
	global_store_dword v[112:113], v114, off
.LBB0_1146:
	s_or_b64 exec, exec, s[14:15]
	v_or_b32_e32 v132, 48, v166
	v_ashrrev_i32_e32 v133, 31, v132
	s_waitcnt lgkmcnt(0)
	v_lshlrev_b64 v[112:113], 11, v[132:133]
	v_lshl_add_u64 v[112:113], s[42:43], 0, v[112:113]
	v_lshl_add_u64 v[134:135], v[158:159], 1, v[112:113]
	global_load_dwordx4 v[116:119], v[134:135], off
	global_load_dwordx4 v[112:115], v[134:135], off offset:256
	v_lshlrev_b32_e32 v138, 16, v140
	v_and_b32_e32 v139, 0xffff0000, v140
	v_add_f32_e32 v108, v108, v138
	v_add_f32_e32 v109, v109, v139
	v_lshlrev_b32_e32 v138, 16, v141
	v_and_b32_e32 v139, 0xffff0000, v141
	v_add_f32_e32 v110, v110, v138
	v_add_f32_e32 v111, v111, v139
	v_lshlrev_b32_e32 v138, 16, v142
	v_and_b32_e32 v139, 0xffff0000, v142
	v_add_f32_e32 v138, v104, v138
	v_add_f32_e32 v139, v105, v139
	v_lshlrev_b32_e32 v104, 16, v143
	v_and_b32_e32 v105, 0xffff0000, v143
	v_add_f32_e32 v140, v106, v104
	v_add_f32_e32 v141, v107, v105
	v_cvt_pk_bf16_f32 v104, v108, v109
	s_nop 0
	v_mul_f32_e32 v106, v109, v109
	v_cvt_pk_bf16_f32 v105, v110, v111
	v_fmac_f32_e32 v106, v108, v108
	s_nop 0
	v_mul_f32_e32 v107, v111, v111
	v_fmac_f32_e32 v107, v110, v110
	v_add_f32_e32 v107, v106, v107
	v_cvt_pk_bf16_f32 v106, v138, v139
	s_nop 0
	s_nop 0
	v_mul_f32_e32 v108, v139, v139
	v_fmac_f32_e32 v108, v138, v138
	v_add_f32_e32 v108, v108, v107
	v_cvt_pk_bf16_f32 v107, v140, v141
	s_nop 0
	global_store_dwordx4 v[192:193], v[104:107], off
	v_mul_f32_e32 v109, v141, v141
	v_fmac_f32_e32 v109, v140, v140
	v_lshlrev_b32_e32 v104, 16, v128
	v_and_b32_e32 v105, 0xffff0000, v128
	v_add_f32_e32 v100, v100, v104
	v_add_f32_e32 v101, v101, v105
	v_lshlrev_b32_e32 v104, 16, v129
	v_and_b32_e32 v105, 0xffff0000, v129
	v_add_f32_e32 v102, v102, v104
	v_add_f32_e32 v103, v103, v105
	v_lshlrev_b32_e32 v104, 16, v130
	v_and_b32_e32 v105, 0xffff0000, v130
	v_add_f32_e32 v96, v96, v104
	v_add_f32_e32 v97, v97, v105
	v_lshlrev_b32_e32 v104, 16, v131
	v_and_b32_e32 v105, 0xffff0000, v131
	v_add_f32_e32 v104, v98, v104
	v_add_f32_e32 v105, v99, v105
	v_cvt_pk_bf16_f32 v98, v100, v101
	v_add_f32_e32 v108, v109, v108
	s_nop 0
	v_mul_f32_e32 v99, v101, v101
	v_fmac_f32_e32 v99, v100, v100
	v_add_f32_e32 v100, v99, v108
	v_cvt_pk_bf16_f32 v99, v102, v103
	s_nop 0
	s_nop 0
	v_mul_f32_e32 v101, v103, v103
	v_fmac_f32_e32 v101, v102, v102
	v_add_f32_e32 v101, v101, v100
	v_cvt_pk_bf16_f32 v100, v96, v97
	s_nop 0
	v_mul_f32_e32 v97, v97, v97
	v_fmac_f32_e32 v97, v96, v96
	v_add_f32_e32 v96, v97, v101
	v_mul_f32_e32 v97, v105, v105
	v_fmac_f32_e32 v97, v104, v104
	v_add_f32_e32 v96, v97, v96
	ds_bpermute_b32 v97, v136, v96
	s_waitcnt lgkmcnt(0)
	v_add_f32_e32 v96, v96, v97
	ds_bpermute_b32 v97, v137, v96
	v_cvt_pk_bf16_f32 v101, v104, v105
	s_nop 0
	global_store_dwordx4 v[192:193], v[98:101], off offset:256
	s_and_saveexec_b64 s[14:15], s[2:3]
	s_cbranch_execz .LBB0_1148
	s_waitcnt lgkmcnt(0)
	v_add_f32_e32 v98, v96, v97
	v_lshlrev_b64 v[96:97], 6, v[190:191]
	v_lshl_add_u64 v[96:97], s[40:41], 0, v[96:97]
	v_lshl_add_u64 v[96:97], s[12:13], 2, v[96:97]
	s_lshl_b32 s90, s35, 2
	v_lshl_add_u64 v[96:97], v[96:97], 0, s[90:91]
	global_store_dword v[96:97], v98, off
.LBB0_1148:
	s_or_b64 exec, exec, s[14:15]
	v_add_u32_e32 v104, 0x80, v166
	v_ashrrev_i32_e32 v105, 31, v104
	s_waitcnt lgkmcnt(0)
	v_lshlrev_b64 v[96:97], 11, v[104:105]
	v_lshl_add_u64 v[96:97], s[42:43], 0, v[96:97]
	v_lshl_add_u64 v[106:107], v[158:159], 1, v[96:97]
	global_load_dwordx4 v[100:103], v[106:107], off
	global_load_dwordx4 v[96:99], v[106:107], off offset:256
	v_lshlrev_b32_e32 v108, 16, v124
	v_and_b32_e32 v109, 0xffff0000, v124
	v_add_f32_e32 v92, v92, v108
	v_add_f32_e32 v93, v93, v109
	v_lshlrev_b32_e32 v108, 16, v125
	v_and_b32_e32 v109, 0xffff0000, v125
	v_add_f32_e32 v94, v94, v108
	v_add_f32_e32 v95, v95, v109
	v_lshlrev_b32_e32 v108, 16, v126
	v_and_b32_e32 v109, 0xffff0000, v126
	v_add_f32_e32 v108, v88, v108
	v_add_f32_e32 v109, v89, v109
	v_lshlrev_b32_e32 v88, 16, v127
	v_and_b32_e32 v89, 0xffff0000, v127
	v_add_f32_e32 v110, v90, v88
	v_add_f32_e32 v111, v91, v89
	v_cvt_pk_bf16_f32 v88, v92, v93
	s_nop 0
	v_mul_f32_e32 v90, v93, v93
	v_cvt_pk_bf16_f32 v89, v94, v95
	v_fmac_f32_e32 v90, v92, v92
	s_nop 0
	v_mul_f32_e32 v91, v95, v95
	v_fmac_f32_e32 v91, v94, v94
	v_add_f32_e32 v91, v90, v91
	v_cvt_pk_bf16_f32 v90, v108, v109
	s_nop 0
	s_nop 0
	v_mul_f32_e32 v92, v109, v109
	v_fmac_f32_e32 v92, v108, v108
	v_add_f32_e32 v92, v92, v91
	v_cvt_pk_bf16_f32 v91, v110, v111
	s_nop 0
	v_and_b32_e32 v94, 0xffff0000, v91
	v_sub_f32_e32 v94, v111, v94
	global_store_dwordx4 v[164:165], v[88:91], off
	v_mul_f32_e32 v93, v111, v111
	v_fmac_f32_e32 v93, v110, v110
	v_lshlrev_b32_e32 v88, 16, v120
	v_and_b32_e32 v89, 0xffff0000, v120
	v_add_f32_e32 v84, v84, v88
	v_add_f32_e32 v85, v85, v89
	v_lshlrev_b32_e32 v88, 16, v121
	v_and_b32_e32 v89, 0xffff0000, v121
	v_add_f32_e32 v86, v86, v88
	v_add_f32_e32 v87, v87, v89
	v_lshlrev_b32_e32 v88, 16, v122
	v_and_b32_e32 v89, 0xffff0000, v122
	v_add_f32_e32 v80, v80, v88
	v_add_f32_e32 v81, v81, v89
	v_lshlrev_b32_e32 v88, 16, v123
	v_and_b32_e32 v89, 0xffff0000, v123
	v_add_f32_e32 v88, v82, v88
	v_add_f32_e32 v89, v83, v89
	v_cvt_pk_bf16_f32 v82, v84, v85
	v_add_f32_e32 v92, v93, v92
	s_nop 0
	v_mul_f32_e32 v83, v85, v85
	v_fmac_f32_e32 v83, v84, v84
	v_add_f32_e32 v84, v83, v92
	v_cvt_pk_bf16_f32 v83, v86, v87
	s_nop 0
	s_nop 0
	v_mul_f32_e32 v85, v87, v87
	v_fmac_f32_e32 v85, v86, v86
	v_add_f32_e32 v85, v85, v84
	v_cvt_pk_bf16_f32 v84, v80, v81
	s_nop 0
	v_mul_f32_e32 v81, v81, v81
	v_fmac_f32_e32 v81, v80, v80
	v_add_f32_e32 v80, v81, v85
	v_mul_f32_e32 v81, v89, v89
	v_fmac_f32_e32 v81, v88, v88
	v_add_f32_e32 v80, v81, v80
	ds_bpermute_b32 v81, v136, v80
	s_waitcnt lgkmcnt(0)
	v_add_f32_e32 v80, v80, v81
	ds_bpermute_b32 v81, v137, v80
	v_cvt_pk_bf16_f32 v85, v88, v89
	s_nop 0
	global_store_dwordx4 v[164:165], v[82:85], off offset:256
	s_and_saveexec_b64 s[14:15], s[2:3]
	s_cbranch_execz .LBB0_1150
	s_waitcnt lgkmcnt(0)
	v_add_f32_e32 v82, v80, v81
	v_lshlrev_b64 v[80:81], 6, v[162:163]
	v_lshl_add_u64 v[80:81], s[40:41], 0, v[80:81]
	v_lshl_add_u64 v[80:81], s[12:13], 2, v[80:81]
	s_lshl_b32 s90, s35, 2
	v_lshl_add_u64 v[80:81], v[80:81], 0, s[90:91]
	global_store_dword v[80:81], v82, off
.LBB0_1150:
	s_or_b64 exec, exec, s[14:15]
	s_waitcnt lgkmcnt(0)
	v_lshl_add_u64 v[80:81], v[158:159], 1, v[160:161]
	s_mov_b64 s[14:15], 0x48000
	v_lshl_add_u64 v[88:89], v[80:81], 0, s[14:15]
	v_add_co_u32_e32 v80, vcc, 0x48000, v80
	s_waitcnt vmcnt(7)
	v_lshlrev_b32_e32 v90, 16, v116
	v_addc_co_u32_e32 v81, vcc, 0, v81, vcc
	global_load_dwordx4 v[84:87], v[80:81], off
	s_nop 0
	global_load_dwordx4 v[80:83], v[88:89], off offset:256
	v_and_b32_e32 v91, 0xffff0000, v116
	v_add_f32_e32 v76, v76, v90
	v_add_f32_e32 v77, v77, v91
	v_lshlrev_b32_e32 v90, 16, v117
	v_and_b32_e32 v91, 0xffff0000, v117
	v_add_f32_e32 v78, v78, v90
	v_add_f32_e32 v79, v79, v91
	v_lshlrev_b32_e32 v90, 16, v118
	v_and_b32_e32 v91, 0xffff0000, v118
	v_add_f32_e32 v90, v72, v90
	v_add_f32_e32 v91, v73, v91
	v_lshlrev_b32_e32 v72, 16, v119
	v_and_b32_e32 v73, 0xffff0000, v119
	v_add_f32_e32 v92, v74, v72
	v_add_f32_e32 v93, v75, v73
	v_cvt_pk_bf16_f32 v72, v76, v77
	s_nop 0
	v_mul_f32_e32 v74, v77, v77
	v_cvt_pk_bf16_f32 v73, v78, v79
	v_fmac_f32_e32 v74, v76, v76
	s_nop 0
	v_mul_f32_e32 v75, v79, v79
	v_fmac_f32_e32 v75, v78, v78
	v_add_f32_e32 v75, v74, v75
	v_cvt_pk_bf16_f32 v74, v90, v91
	s_nop 0
	s_nop 0
	v_mul_f32_e32 v76, v91, v91
	v_fmac_f32_e32 v76, v90, v90
	v_add_f32_e32 v76, v76, v75
	v_cvt_pk_bf16_f32 v75, v92, v93
	s_nop 0
	global_store_dwordx4 v[134:135], v[72:75], off
	v_mul_f32_e32 v77, v93, v93
	v_fmac_f32_e32 v77, v92, v92
	s_waitcnt vmcnt(9)
	v_lshlrev_b32_e32 v72, 16, v112
	v_and_b32_e32 v73, 0xffff0000, v112
	v_add_f32_e32 v68, v68, v72
	v_add_f32_e32 v69, v69, v73
	v_lshlrev_b32_e32 v72, 16, v113
	v_and_b32_e32 v73, 0xffff0000, v113
	v_add_f32_e32 v70, v70, v72
	v_add_f32_e32 v71, v71, v73
	v_lshlrev_b32_e32 v72, 16, v114
	v_and_b32_e32 v73, 0xffff0000, v114
	v_add_f32_e32 v64, v64, v72
	v_add_f32_e32 v65, v65, v73
	v_lshlrev_b32_e32 v72, 16, v115
	v_and_b32_e32 v73, 0xffff0000, v115
	v_add_f32_e32 v72, v66, v72
	v_add_f32_e32 v73, v67, v73
	v_cvt_pk_bf16_f32 v66, v68, v69
	v_add_f32_e32 v76, v77, v76
	s_nop 0
	v_mul_f32_e32 v67, v69, v69
	v_fmac_f32_e32 v67, v68, v68
	v_add_f32_e32 v68, v67, v76
	v_cvt_pk_bf16_f32 v67, v70, v71
	s_nop 0
	s_nop 0
	v_mul_f32_e32 v69, v71, v71
	v_fmac_f32_e32 v69, v70, v70
	v_add_f32_e32 v69, v69, v68
	v_cvt_pk_bf16_f32 v68, v64, v65
	s_nop 0
	v_mul_f32_e32 v65, v65, v65
	v_fmac_f32_e32 v65, v64, v64
	v_add_f32_e32 v64, v65, v69
	v_mul_f32_e32 v65, v73, v73
	v_fmac_f32_e32 v65, v72, v72
	v_add_f32_e32 v64, v65, v64
	ds_bpermute_b32 v65, v136, v64
	s_waitcnt lgkmcnt(0)
	v_add_f32_e32 v64, v64, v65
	ds_bpermute_b32 v65, v137, v64
	v_cvt_pk_bf16_f32 v69, v72, v73
	s_nop 0
	global_store_dwordx4 v[134:135], v[66:69], off offset:256
	s_and_saveexec_b64 s[14:15], s[2:3]
	s_cbranch_execz .LBB0_1152
	s_waitcnt lgkmcnt(0)
	v_add_f32_e32 v66, v64, v65
	v_lshlrev_b64 v[64:65], 6, v[132:133]
	v_lshl_add_u64 v[64:65], s[40:41], 0, v[64:65]
	v_lshl_add_u64 v[64:65], s[12:13], 2, v[64:65]
	s_lshl_b32 s90, s35, 2
	v_lshl_add_u64 v[64:65], v[64:65], 0, s[90:91]
	global_store_dword v[64:65], v66, off
.LBB0_1152:
	s_or_b64 exec, exec, s[14:15]
	v_or_b32_e32 v72, 32, v104
	v_ashrrev_i32_e32 v73, 31, v72
	s_waitcnt lgkmcnt(0)
	v_lshlrev_b64 v[64:65], 11, v[72:73]
	v_lshl_add_u64 v[64:65], s[42:43], 0, v[64:65]
	v_lshl_add_u64 v[74:75], v[158:159], 1, v[64:65]
	global_load_dwordx4 v[68:71], v[74:75], off
	global_load_dwordx4 v[64:67], v[74:75], off offset:256
	s_waitcnt vmcnt(9)
	v_lshlrev_b32_e32 v76, 16, v100
	v_and_b32_e32 v77, 0xffff0000, v100
	v_add_f32_e32 v60, v60, v76
	v_add_f32_e32 v61, v61, v77
	v_lshlrev_b32_e32 v76, 16, v101
	v_and_b32_e32 v77, 0xffff0000, v101
	v_add_f32_e32 v62, v62, v76
	v_add_f32_e32 v63, v63, v77
	v_lshlrev_b32_e32 v76, 16, v102
	v_and_b32_e32 v77, 0xffff0000, v102
	v_add_f32_e32 v76, v56, v76
	v_add_f32_e32 v77, v57, v77
	v_lshlrev_b32_e32 v56, 16, v103
	v_and_b32_e32 v57, 0xffff0000, v103
	v_add_f32_e32 v78, v58, v56
	v_add_f32_e32 v79, v59, v57
	v_cvt_pk_bf16_f32 v56, v60, v61
	s_nop 0
	v_mul_f32_e32 v58, v61, v61
	v_cvt_pk_bf16_f32 v57, v62, v63
	v_fmac_f32_e32 v58, v60, v60
	s_nop 0
	v_mul_f32_e32 v59, v63, v63
	v_fmac_f32_e32 v59, v62, v62
	v_add_f32_e32 v59, v58, v59
	v_cvt_pk_bf16_f32 v58, v76, v77
	s_nop 0
	s_nop 0
	v_mul_f32_e32 v60, v77, v77
	v_fmac_f32_e32 v60, v76, v76
	v_add_f32_e32 v60, v60, v59
	v_cvt_pk_bf16_f32 v59, v78, v79
	s_nop 0
	global_store_dwordx4 v[106:107], v[56:59], off
	v_mul_f32_e32 v61, v79, v79
	v_fmac_f32_e32 v61, v78, v78
	s_waitcnt vmcnt(9)
	v_lshlrev_b32_e32 v56, 16, v96
	v_and_b32_e32 v57, 0xffff0000, v96
	v_add_f32_e32 v52, v52, v56
	v_add_f32_e32 v53, v53, v57
	v_lshlrev_b32_e32 v56, 16, v97
	v_and_b32_e32 v57, 0xffff0000, v97
	v_add_f32_e32 v54, v54, v56
	v_add_f32_e32 v55, v55, v57
	v_lshlrev_b32_e32 v56, 16, v98
	v_and_b32_e32 v57, 0xffff0000, v98
	v_add_f32_e32 v48, v48, v56
	v_add_f32_e32 v49, v49, v57
	v_lshlrev_b32_e32 v56, 16, v99
	v_and_b32_e32 v57, 0xffff0000, v99
	v_add_f32_e32 v56, v50, v56
	v_add_f32_e32 v57, v51, v57
	v_cvt_pk_bf16_f32 v50, v52, v53
	v_add_f32_e32 v60, v61, v60
	s_nop 0
	v_mul_f32_e32 v51, v53, v53
	v_fmac_f32_e32 v51, v52, v52
	v_add_f32_e32 v52, v51, v60
	v_cvt_pk_bf16_f32 v51, v54, v55
	s_nop 0
	s_nop 0
	v_mul_f32_e32 v53, v55, v55
	v_fmac_f32_e32 v53, v54, v54
	v_add_f32_e32 v53, v53, v52
	v_cvt_pk_bf16_f32 v52, v48, v49
	s_nop 0
	v_mul_f32_e32 v49, v49, v49
	v_fmac_f32_e32 v49, v48, v48
	v_add_f32_e32 v48, v49, v53
	v_mul_f32_e32 v49, v57, v57
	v_fmac_f32_e32 v49, v56, v56
	v_add_f32_e32 v48, v49, v48
	ds_bpermute_b32 v49, v136, v48
	s_waitcnt lgkmcnt(0)
	v_add_f32_e32 v48, v48, v49
	ds_bpermute_b32 v49, v137, v48
	v_cvt_pk_bf16_f32 v53, v56, v57
	s_nop 0
	global_store_dwordx4 v[106:107], v[50:53], off offset:256
	s_and_saveexec_b64 s[14:15], s[2:3]
	s_cbranch_execz .LBB0_1154
	s_waitcnt lgkmcnt(0)
	v_add_f32_e32 v50, v48, v49
	v_lshlrev_b64 v[48:49], 6, v[104:105]
	v_lshl_add_u64 v[48:49], s[40:41], 0, v[48:49]
	v_lshl_add_u64 v[48:49], s[12:13], 2, v[48:49]
	s_lshl_b32 s90, s35, 2
	v_lshl_add_u64 v[48:49], v[48:49], 0, s[90:91]
	global_store_dword v[48:49], v50, off
.LBB0_1154:
	s_or_b64 exec, exec, s[14:15]
	v_or_b32_e32 v56, 48, v104
	v_ashrrev_i32_e32 v57, 31, v56
	s_waitcnt lgkmcnt(0)
	v_lshlrev_b64 v[48:49], 11, v[56:57]
	v_lshl_add_u64 v[48:49], s[42:43], 0, v[48:49]
	v_lshl_add_u64 v[58:59], v[158:159], 1, v[48:49]
	global_load_dwordx4 v[52:55], v[58:59], off
	global_load_dwordx4 v[48:51], v[58:59], off offset:256
	s_waitcnt vmcnt(9)
	v_lshlrev_b32_e32 v60, 16, v84
	v_and_b32_e32 v61, 0xffff0000, v84
	v_add_f32_e32 v44, v44, v60
	v_add_f32_e32 v45, v45, v61
	v_lshlrev_b32_e32 v60, 16, v85
	v_and_b32_e32 v61, 0xffff0000, v85
	v_add_f32_e32 v46, v46, v60
	v_add_f32_e32 v47, v47, v61
	v_lshlrev_b32_e32 v60, 16, v86
	v_and_b32_e32 v61, 0xffff0000, v86
	v_add_f32_e32 v60, v40, v60
	v_add_f32_e32 v61, v41, v61
	v_lshlrev_b32_e32 v40, 16, v87
	v_and_b32_e32 v41, 0xffff0000, v87
	v_add_f32_e32 v62, v42, v40
	v_add_f32_e32 v63, v43, v41
	v_cvt_pk_bf16_f32 v40, v44, v45
	s_nop 0
	v_mul_f32_e32 v42, v45, v45
	v_cvt_pk_bf16_f32 v41, v46, v47
	v_fmac_f32_e32 v42, v44, v44
	s_nop 0
	v_mul_f32_e32 v43, v47, v47
	v_fmac_f32_e32 v43, v46, v46
	v_add_f32_e32 v43, v42, v43
	v_cvt_pk_bf16_f32 v42, v60, v61
	s_nop 0
	s_nop 0
	v_mul_f32_e32 v44, v61, v61
	v_fmac_f32_e32 v44, v60, v60
	v_add_f32_e32 v44, v44, v43
	v_cvt_pk_bf16_f32 v43, v62, v63
	s_nop 0
	v_and_b32_e32 v46, 0xffff0000, v43
	v_sub_f32_e32 v46, v63, v46
	global_store_dwordx4 v[88:89], v[40:43], off
	v_mul_f32_e32 v45, v63, v63
	v_fmac_f32_e32 v45, v62, v62
	s_waitcnt vmcnt(9)
	v_lshlrev_b32_e32 v40, 16, v80
	v_and_b32_e32 v41, 0xffff0000, v80
	v_add_f32_e32 v36, v36, v40
	v_add_f32_e32 v37, v37, v41
	v_lshlrev_b32_e32 v40, 16, v81
	v_and_b32_e32 v41, 0xffff0000, v81
	v_add_f32_e32 v38, v38, v40
	v_add_f32_e32 v39, v39, v41
	v_lshlrev_b32_e32 v40, 16, v82
	v_and_b32_e32 v41, 0xffff0000, v82
	v_add_f32_e32 v32, v32, v40
	v_add_f32_e32 v33, v33, v41
	v_lshlrev_b32_e32 v40, 16, v83
	v_and_b32_e32 v41, 0xffff0000, v83
	v_add_f32_e32 v40, v34, v40
	v_add_f32_e32 v41, v35, v41
	v_cvt_pk_bf16_f32 v34, v36, v37
	v_add_f32_e32 v44, v45, v44
	s_nop 0
	v_mul_f32_e32 v35, v37, v37
	v_fmac_f32_e32 v35, v36, v36
	v_add_f32_e32 v36, v35, v44
	v_cvt_pk_bf16_f32 v35, v38, v39
	s_nop 0
	v_and_b32_e32 v42, 0xffff0000, v35
	v_sub_f32_e32 v42, v39, v42
	s_nop 0
	v_mul_f32_e32 v37, v39, v39
	v_fmac_f32_e32 v37, v38, v38
	v_add_f32_e32 v37, v37, v36
	v_cvt_pk_bf16_f32 v36, v32, v33
	s_nop 0
	v_mul_f32_e32 v33, v33, v33
	v_fmac_f32_e32 v33, v32, v32
	v_add_f32_e32 v32, v33, v37
	v_mul_f32_e32 v33, v41, v41
	v_fmac_f32_e32 v33, v40, v40
	v_add_f32_e32 v32, v33, v32
	ds_bpermute_b32 v33, v136, v32
	s_waitcnt lgkmcnt(0)
	v_add_f32_e32 v32, v32, v33
	ds_bpermute_b32 v33, v137, v32
	v_cvt_pk_bf16_f32 v37, v40, v41
	s_nop 0
	v_lshlrev_b32_e32 v38, 16, v37
	v_sub_f32_e32 v38, v40, v38
	v_and_b32_e32 v39, 0xffff0000, v37
	v_sub_f32_e32 v39, v41, v39
	v_cvt_pk_bf16_f32 v38, v38, v39
	global_store_dwordx4 v[88:89], v[34:37], off offset:256
	s_and_saveexec_b64 s[14:15], s[2:3]
	s_cbranch_execz .LBB0_1156
	v_or_b32_e32 v34, 16, v104
	v_ashrrev_i32_e32 v35, 31, v34
	s_waitcnt lgkmcnt(0)
	v_add_f32_e32 v36, v32, v33
	v_lshlrev_b64 v[32:33], 6, v[34:35]
	v_lshl_add_u64 v[32:33], s[40:41], 0, v[32:33]
	v_lshl_add_u64 v[32:33], s[12:13], 2, v[32:33]
	s_lshl_b32 s90, s35, 2
	v_lshl_add_u64 v[32:33], v[32:33], 0, s[90:91]
	global_store_dword v[32:33], v36, off
.LBB0_1156:
	s_or_b64 exec, exec, s[14:15]
	s_waitcnt vmcnt(7)
	v_lshlrev_b32_e32 v32, 16, v68
	s_waitcnt lgkmcnt(0)
	v_and_b32_e32 v33, 0xffff0000, v68
	v_add_f32_e32 v28, v28, v32
	v_add_f32_e32 v29, v29, v33
	v_lshlrev_b32_e32 v32, 16, v69
	v_and_b32_e32 v33, 0xffff0000, v69
	v_add_f32_e32 v30, v30, v32
	v_add_f32_e32 v31, v31, v33
	v_lshlrev_b32_e32 v32, 16, v70
	v_and_b32_e32 v33, 0xffff0000, v70
	v_add_f32_e32 v32, v24, v32
	v_add_f32_e32 v33, v25, v33
	v_lshlrev_b32_e32 v24, 16, v71
	v_and_b32_e32 v25, 0xffff0000, v71
	v_add_f32_e32 v34, v26, v24
	v_add_f32_e32 v35, v27, v25
	v_cvt_pk_bf16_f32 v24, v28, v29
	s_nop 0
	v_mul_f32_e32 v26, v29, v29
	v_cvt_pk_bf16_f32 v25, v30, v31
	v_fmac_f32_e32 v26, v28, v28
	s_nop 0
	v_mul_f32_e32 v27, v31, v31
	v_fmac_f32_e32 v27, v30, v30
	v_add_f32_e32 v27, v26, v27
	v_cvt_pk_bf16_f32 v26, v32, v33
	s_nop 0
	s_nop 0
	v_mul_f32_e32 v28, v33, v33
	v_fmac_f32_e32 v28, v32, v32
	v_add_f32_e32 v28, v28, v27
	v_cvt_pk_bf16_f32 v27, v34, v35
	s_nop 0
	v_and_b32_e32 v30, 0xffff0000, v27
	v_sub_f32_e32 v30, v35, v30
	global_store_dwordx4 v[74:75], v[24:27], off
	v_mul_f32_e32 v29, v35, v35
	v_fmac_f32_e32 v29, v34, v34
	s_waitcnt vmcnt(7)
	v_lshlrev_b32_e32 v24, 16, v64
	v_and_b32_e32 v25, 0xffff0000, v64
	v_add_f32_e32 v20, v20, v24
	v_add_f32_e32 v21, v21, v25
	v_lshlrev_b32_e32 v24, 16, v65
	v_and_b32_e32 v25, 0xffff0000, v65
	v_add_f32_e32 v22, v22, v24
	v_add_f32_e32 v23, v23, v25
	v_lshlrev_b32_e32 v24, 16, v66
	v_and_b32_e32 v25, 0xffff0000, v66
	v_add_f32_e32 v16, v16, v24
	v_add_f32_e32 v17, v17, v25
	v_lshlrev_b32_e32 v24, 16, v67
	v_and_b32_e32 v25, 0xffff0000, v67
	v_add_f32_e32 v24, v18, v24
	v_add_f32_e32 v25, v19, v25
	v_cvt_pk_bf16_f32 v18, v20, v21
	v_add_f32_e32 v28, v29, v28
	s_nop 0
	v_mul_f32_e32 v19, v21, v21
	v_fmac_f32_e32 v19, v20, v20
	v_add_f32_e32 v20, v19, v28
	v_cvt_pk_bf16_f32 v19, v22, v23
	s_nop 0
	v_and_b32_e32 v26, 0xffff0000, v19
	v_sub_f32_e32 v26, v23, v26
	s_nop 0
	v_mul_f32_e32 v21, v23, v23
	v_fmac_f32_e32 v21, v22, v22
	v_add_f32_e32 v21, v21, v20
	v_cvt_pk_bf16_f32 v20, v16, v17
	s_nop 0
	v_mul_f32_e32 v17, v17, v17
	v_fmac_f32_e32 v17, v16, v16
	v_add_f32_e32 v16, v17, v21
	v_mul_f32_e32 v17, v25, v25
	v_fmac_f32_e32 v17, v24, v24
	v_add_f32_e32 v16, v17, v16
	ds_bpermute_b32 v17, v136, v16
	s_waitcnt lgkmcnt(0)
	v_add_f32_e32 v16, v16, v17
	ds_bpermute_b32 v17, v137, v16
	v_cvt_pk_bf16_f32 v21, v24, v25
	s_nop 0
	v_lshlrev_b32_e32 v22, 16, v21
	v_sub_f32_e32 v22, v24, v22
	v_and_b32_e32 v23, 0xffff0000, v21
	v_sub_f32_e32 v23, v25, v23
	v_cvt_pk_bf16_f32 v22, v22, v23
	global_store_dwordx4 v[74:75], v[18:21], off offset:256
	s_and_saveexec_b64 s[14:15], s[2:3]
	s_cbranch_execz .LBB0_1158
	s_waitcnt lgkmcnt(0)
	v_add_f32_e32 v18, v16, v17
	v_lshlrev_b64 v[16:17], 6, v[72:73]
	v_lshl_add_u64 v[16:17], s[40:41], 0, v[16:17]
	v_lshl_add_u64 v[16:17], s[12:13], 2, v[16:17]
	s_lshl_b32 s90, s35, 2
	v_lshl_add_u64 v[16:17], v[16:17], 0, s[90:91]
	global_store_dword v[16:17], v18, off
.LBB0_1158:
	s_or_b64 exec, exec, s[14:15]
	s_waitcnt vmcnt(5)
	v_lshlrev_b32_e32 v16, 16, v52
	s_waitcnt lgkmcnt(0)
	v_and_b32_e32 v17, 0xffff0000, v52
	v_add_f32_e32 v12, v12, v16
	v_add_f32_e32 v13, v13, v17
	v_lshlrev_b32_e32 v16, 16, v53
	v_and_b32_e32 v17, 0xffff0000, v53
	v_add_f32_e32 v14, v14, v16
	v_add_f32_e32 v15, v15, v17
	v_lshlrev_b32_e32 v16, 16, v54
	v_and_b32_e32 v17, 0xffff0000, v54
	v_add_f32_e32 v16, v8, v16
	v_add_f32_e32 v17, v9, v17
	v_lshlrev_b32_e32 v8, 16, v55
	v_and_b32_e32 v9, 0xffff0000, v55
	v_add_f32_e32 v18, v10, v8
	v_add_f32_e32 v19, v11, v9
	v_cvt_pk_bf16_f32 v8, v12, v13
	s_nop 0
	v_mul_f32_e32 v10, v13, v13
	v_cvt_pk_bf16_f32 v9, v14, v15
	v_fmac_f32_e32 v10, v12, v12
	s_nop 0
	v_mul_f32_e32 v11, v15, v15
	v_fmac_f32_e32 v11, v14, v14
	v_add_f32_e32 v11, v10, v11
	v_cvt_pk_bf16_f32 v10, v16, v17
	s_nop 0
	s_nop 0
	v_mul_f32_e32 v12, v17, v17
	v_fmac_f32_e32 v12, v16, v16
	v_add_f32_e32 v12, v12, v11
	v_cvt_pk_bf16_f32 v11, v18, v19
	s_nop 0
	v_and_b32_e32 v14, 0xffff0000, v11
	v_sub_f32_e32 v14, v19, v14
	global_store_dwordx4 v[58:59], v[8:11], off
	v_mul_f32_e32 v13, v19, v19
	v_fmac_f32_e32 v13, v18, v18
	s_waitcnt vmcnt(5)
	v_lshlrev_b32_e32 v8, 16, v48
	v_and_b32_e32 v9, 0xffff0000, v48
	v_add_f32_e32 v4, v4, v8
	v_add_f32_e32 v5, v5, v9
	v_lshlrev_b32_e32 v8, 16, v49
	v_and_b32_e32 v9, 0xffff0000, v49
	v_add_f32_e32 v6, v6, v8
	v_add_f32_e32 v7, v7, v9
	v_lshlrev_b32_e32 v8, 16, v50
	v_and_b32_e32 v9, 0xffff0000, v50
	v_add_f32_e32 v0, v0, v8
	v_add_f32_e32 v1, v1, v9
	v_lshlrev_b32_e32 v8, 16, v51
	v_and_b32_e32 v9, 0xffff0000, v51
	v_add_f32_e32 v8, v2, v8
	v_add_f32_e32 v9, v3, v9
	v_cvt_pk_bf16_f32 v2, v4, v5
	v_add_f32_e32 v12, v13, v12
	s_nop 0
	v_mul_f32_e32 v3, v5, v5
	v_fmac_f32_e32 v3, v4, v4
	v_add_f32_e32 v4, v3, v12
	v_cvt_pk_bf16_f32 v3, v6, v7
	s_nop 0
	v_and_b32_e32 v10, 0xffff0000, v3
	v_sub_f32_e32 v10, v7, v10
	s_nop 0
	v_mul_f32_e32 v5, v7, v7
	v_fmac_f32_e32 v5, v6, v6
	v_add_f32_e32 v5, v5, v4
	v_cvt_pk_bf16_f32 v4, v0, v1
	s_nop 0
	v_mul_f32_e32 v1, v1, v1
	v_fmac_f32_e32 v1, v0, v0
	v_add_f32_e32 v0, v1, v5
	v_mul_f32_e32 v1, v9, v9
	v_fmac_f32_e32 v1, v8, v8
	v_add_f32_e32 v0, v1, v0
	ds_bpermute_b32 v1, v136, v0
	s_waitcnt lgkmcnt(0)
	v_add_f32_e32 v0, v0, v1
	ds_bpermute_b32 v1, v137, v0
	v_cvt_pk_bf16_f32 v5, v8, v9
	s_nop 0
	v_lshlrev_b32_e32 v6, 16, v5
	v_sub_f32_e32 v6, v8, v6
	v_and_b32_e32 v7, 0xffff0000, v5
	v_sub_f32_e32 v7, v9, v7
	v_cvt_pk_bf16_f32 v6, v6, v7
	global_store_dwordx4 v[58:59], v[2:5], off offset:256
	s_and_saveexec_b64 s[14:15], s[2:3]
	s_cbranch_execz .LBB0_1160
	s_waitcnt lgkmcnt(0)
	v_add_f32_e32 v2, v0, v1
	v_lshlrev_b64 v[0:1], 6, v[56:57]
	v_lshl_add_u64 v[0:1], s[40:41], 0, v[0:1]
	v_lshl_add_u64 v[0:1], s[12:13], 2, v[0:1]
	s_lshl_b32 s90, s35, 2
	v_lshl_add_u64 v[0:1], v[0:1], 0, s[90:91]
	global_store_dword v[0:1], v2, off
